# SSD: fully masked key-tile pairs skipped per wave in G=C.B^T (7 regenerated variants, exact lgkmcnt) and in M.Xdt slabs
# speedup vs baseline: 1.0187x; 1.0092x over previous
; #define LAS __attribute__((address_space(3)))
; __device__ __forceinline__ void phase_C1(const Args& a, unsigned char* ws, const int bid, int l, LAS unsigned char* lds, int tid, int wave, int lane) {
;     ...
;             {
;                 bf16x8 cqv[2], bq[2][4], hq[2][2];
;     ...
;                 SSD_LDH(0, 0);
; #pragma unroll
;                 for (int h2 = 0; h2 < 8; ++h2) { const int cb = h2 & 1, s_ = h2 >> 1, hf_ = h2 & 1;
;                     if (h2 < 7) SSD_LDH(cb ^ 1, h2 + 1);
;                     __builtin_amdgcn_sched_barrier(0);
; #pragma unroll
;                     for (int k = 0; k < 4; ++k) accA[4 * hf_ + k] = MFMA16(bq[cb][k], cqv[s_ & 1], accA[4 * hf_ + k]);
; #pragma unroll
;                     for (int p = 0; p < 2; ++p) accC[2 * hf_ + p] = MFMA16(hq[cb][p], cqv[s_ & 1], accC[2 * hf_ + p]);
;                     __builtin_amdgcn_sched_barrier(0); }
;     ...
;             }
;             { const float etot = __expf(totp[0]);
; #pragma unroll
;               for (int j = 0; j < 4; ++j) Hacc[j] = Hacc[j] * etot;
; #pragma unroll
;               for (int s = 0; s < 4; ++s) { const s16x4 xlo = TRX(L_X, 32 * s, 16 * wr, 0), xhi = TRX(L_X, 32 * s, 16 * wr, 1);
;                   const f32x4 w0 = *(const LAS f32x4*)(wgt + s * 32 + fq * 8), w1 = *(const LAS f32x4*)(wgt + s * 32 + fq * 8 + 4);
;                   s16x4 blo[4], bhi[4];
; #pragma unroll
;                   for (int j = 0; j < 4; ++j) { blo[j] = TRB(L_B, 32 * s, 16 * (4 * wc + j), 0); bhi[j] = TRB(L_B, 32 * s, 16 * (4 * wc + j), 1); }
;                   __builtin_amdgcn_sched_barrier(0);
;                   const u32x2 xl = __builtin_bit_cast(u32x2, xlo), xh = __builtin_bit_cast(u32x2, xhi);
;                   u32x4 xs; xs.x = cvt_pk_bf16(bflo(xl.x) * w0.x, bfhi(xl.x) * w0.y); xs.y = cvt_pk_bf16(bflo(xl.y) * w0.z, bfhi(xl.y) * w0.w);
;                   xs.z = cvt_pk_bf16(bflo(xh.x) * w1.x, bfhi(xh.x) * w1.y); xs.w = cvt_pk_bf16(bflo(xh.y) * w1.z, bfhi(xh.y) * w1.w);
;                   const bf16x8 xq = __builtin_bit_cast(bf16x8, xs);
; #pragma unroll
;                   for (int j = 0; j < 4; ++j) { const bf16x8 bt = (bf16x8){blo[j].x, blo[j].y, blo[j].z, blo[j].w, bhi[j].x, bhi[j].y, bhi[j].z, bhi[j].w};
;                       Hacc[j] = MFMA16(bt, xq, Hacc[j]); }
;                   __builtin_amdgcn_sched_barrier(0); } }
.LBB0_121:
	v_readfirstlane_b32 vcc_lo, v164
	s_nop 3
	s_cmp_lt_u32 vcc_lo, 0x100
	s_cbranch_scc0 .Lssd_alt_order
	s_branch .Lssd_A_dispatch
.Lssd_A_ret_main:
	v_mov_b32_e32 v116, 0x22e00
	ds_read_b128 v[244:247], v116
	ds_read_b128 v[248:251], v116 offset:16
	ds_read_b128 v[216:219], v133
	ds_read_b128 v[220:223], v134
	ds_read_b128 v[224:227], v135
	ds_read_b128 v[228:231], v136
	ds_read_b128 v[232:235], v137
	ds_read_b128 v[236:239], v138
	ds_read_b128 v[240:243], v139
	ds_read_b128 v[212:215], v132
	v_mov_b32_e32 v116, s87
	ds_read_b32 v116, v116
	s_waitcnt lgkmcnt(0)
	v_mul_f32_e32 v116, 0x3fb8aa3b, v116
	v_exp_f32_e32 v116, v116
	s_nop 0
	v_pk_mul_f32 v[42:43], v[42:43], v[116:117] op_sel_hi:[1,0]
	v_pk_mul_f32 v[40:41], v[40:41], v[116:117] op_sel_hi:[1,0]
	v_pk_mul_f32 v[46:47], v[46:47], v[116:117] op_sel_hi:[1,0]
	v_pk_mul_f32 v[44:45], v[44:45], v[116:117] op_sel_hi:[1,0]
	v_pk_mul_f32 v[50:51], v[50:51], v[116:117] op_sel_hi:[1,0]
	v_pk_mul_f32 v[48:49], v[48:49], v[116:117] op_sel_hi:[1,0]
	v_pk_mul_f32 v[54:55], v[54:55], v[116:117] op_sel_hi:[1,0]
	v_pk_mul_f32 v[52:53], v[52:53], v[116:117] op_sel_hi:[1,0]
	ds_read_b64_tr_b16 v[116:117], v140
	ds_read_b64_tr_b16 v[192:193], v140 offset:576
	ds_read_b128 v[168:171], v125
	ds_read_b128 v[172:175], v125 offset:16
	ds_read_b64_tr_b16 v[178:179], v141 offset:35904
	ds_read_b64_tr_b16 v[176:177], v141 offset:34816
	ds_read_b64_tr_b16 v[180:181], v141 offset:34848
	ds_read_b64_tr_b16 v[182:183], v141 offset:35936
	ds_read_b64_tr_b16 v[184:185], v141 offset:34880
	ds_read_b64_tr_b16 v[186:187], v141 offset:35968
	ds_read_b64_tr_b16 v[188:189], v141 offset:34912
	ds_read_b64_tr_b16 v[190:191], v141 offset:36000
	s_waitcnt lgkmcnt(11)
	v_lshlrev_b32_e32 v194, 16, v116
	v_and_b32_e32 v116, 0xffff0000, v116
	s_waitcnt lgkmcnt(9)
	v_mul_f32_e32 v168, v168, v194
	v_mul_f32_e32 v116, v169, v116
	v_cvt_pk_bf16_f32 v168, v168, v116
	v_lshlrev_b32_e32 v116, 16, v117
	v_and_b32_e32 v117, 0xffff0000, v117
	v_mul_f32_e32 v116, v170, v116
	v_mul_f32_e32 v117, v171, v117
	v_cvt_pk_bf16_f32 v169, v116, v117
	v_lshlrev_b32_e32 v116, 16, v192
	v_and_b32_e32 v117, 0xffff0000, v192
	s_waitcnt lgkmcnt(8)
	v_mul_f32_e32 v116, v172, v116
	v_mul_f32_e32 v117, v173, v117
	v_cvt_pk_bf16_f32 v170, v116, v117
	v_lshlrev_b32_e32 v116, 16, v193
	v_and_b32_e32 v117, 0xffff0000, v193
	v_mul_f32_e32 v116, v174, v116
	v_mul_f32_e32 v117, v175, v117
	v_cvt_pk_bf16_f32 v171, v116, v117
	s_waitcnt lgkmcnt(6)
	v_mfma_f32_16x16x32_bf16 v[40:43], v[176:179], v[168:171], v[40:43]
	s_waitcnt lgkmcnt(4)
	v_mfma_f32_16x16x32_bf16 v[44:47], v[180:183], v[168:171], v[44:47]
	s_waitcnt lgkmcnt(2)
	v_mfma_f32_16x16x32_bf16 v[48:51], v[184:187], v[168:171], v[48:51]
	s_waitcnt lgkmcnt(0)
	v_mfma_f32_16x16x32_bf16 v[52:55], v[188:191], v[168:171], v[52:55]
	ds_read_b128 v[168:171], v125 offset:128
	ds_read_b128 v[172:175], v125 offset:144
	ds_read_b64_tr_b16 v[116:117], v140 offset:4608
	ds_read_b64_tr_b16 v[192:193], v140 offset:5184
	ds_read_b64_tr_b16 v[176:177], v141 offset:43520
	ds_read_b64_tr_b16 v[180:181], v141 offset:43552
	ds_read_b64_tr_b16 v[178:179], v141 offset:44608
	ds_read_b64_tr_b16 v[182:183], v141 offset:44640
	ds_read_b64_tr_b16 v[184:185], v141 offset:43584
	ds_read_b64_tr_b16 v[188:189], v141 offset:43616
	ds_read_b64_tr_b16 v[186:187], v141 offset:44672
	ds_read_b64_tr_b16 v[190:191], v141 offset:44704
	s_waitcnt lgkmcnt(9)
	v_lshlrev_b32_e32 v194, 16, v116
	v_and_b32_e32 v116, 0xffff0000, v116
	v_mul_f32_e32 v168, v168, v194
	v_mul_f32_e32 v116, v169, v116
	v_cvt_pk_bf16_f32 v168, v168, v116
	v_lshlrev_b32_e32 v116, 16, v117
	v_and_b32_e32 v117, 0xffff0000, v117
	v_mul_f32_e32 v116, v170, v116
	v_mul_f32_e32 v117, v171, v117
	v_cvt_pk_bf16_f32 v169, v116, v117
	s_waitcnt lgkmcnt(8)
; #define LAS __attribute__((address_space(3)))
; __device__ __forceinline__ unsigned cvt_pk_bf16(float lo, float hi) { unsigned r; asm volatile("v_cvt_pk_bf16_f32 %0, %1, %2" : "=v"(r) : "v"(lo), "v"(hi)); return r; }
; #define MFMA16(a, b, c) __builtin_amdgcn_mfma_f32_16x16x32_bf16((a), (b), (c), 0, 0, 0)
; #define TRB(base, krow0, col0, t) __builtin_amdgcn_ds_read_tr16_b64_v4i16((LAS s16x4*)((base) + trB + ((krow0) + 4 * (t)) * 272 + (col0) * 2))
; #define TRX(base, krow0, col0, t) __builtin_amdgcn_ds_read_tr16_b64_v4i16((LAS s16x4*)((base) + trX + ((krow0) + 4 * (t)) * 144 + (col0) * 2))
; __device__ __forceinline__ void phase_C1(const Args& a, unsigned char* ws, const int bid, int l, LAS unsigned char* lds, int tid, int wave, int lane) {
;     ...
;               for (int s = 0; s < 4; ++s) { const s16x4 xlo = TRX(L_X, 32 * s, 16 * wr, 0), xhi = TRX(L_X, 32 * s, 16 * wr, 1);
;                   const f32x4 w0 = *(const LAS f32x4*)(wgt + s * 32 + fq * 8), w1 = *(const LAS f32x4*)(wgt + s * 32 + fq * 8 + 4);
;                   s16x4 blo[4], bhi[4];
; #pragma unroll
;                   for (int j = 0; j < 4; ++j) { blo[j] = TRB(L_B, 32 * s, 16 * (4 * wc + j), 0); bhi[j] = TRB(L_B, 32 * s, 16 * (4 * wc + j), 1); }
;                   __builtin_amdgcn_sched_barrier(0);
;                   const u32x2 xl = __builtin_bit_cast(u32x2, xlo), xh = __builtin_bit_cast(u32x2, xhi);
;                   u32x4 xs; xs.x = cvt_pk_bf16(bflo(xl.x) * w0.x, bfhi(xl.x) * w0.y); xs.y = cvt_pk_bf16(bflo(xl.y) * w0.z, bfhi(xl.y) * w0.w);
;                   xs.z = cvt_pk_bf16(bflo(xh.x) * w1.x, bfhi(xh.x) * w1.y); xs.w = cvt_pk_bf16(bflo(xh.y) * w1.z, bfhi(xh.y) * w1.w);
;                   const bf16x8 xq = __builtin_bit_cast(bf16x8, xs);
; #pragma unroll
;                   for (int j = 0; j < 4; ++j) { const bf16x8 bt = (bf16x8){blo[j].x, blo[j].y, blo[j].z, blo[j].w, bhi[j].x, bhi[j].y, bhi[j].z, bhi[j].w};
;                       Hacc[j] = MFMA16(bt, xq, Hacc[j]); }
;                   __builtin_amdgcn_sched_barrier(0); } }
	v_lshlrev_b32_e32 v116, 16, v192
	v_and_b32_e32 v117, 0xffff0000, v192
	v_mul_f32_e32 v116, v172, v116
	v_mul_f32_e32 v117, v173, v117
	v_cvt_pk_bf16_f32 v170, v116, v117
	v_lshlrev_b32_e32 v116, 16, v193
	v_and_b32_e32 v117, 0xffff0000, v193
	v_mul_f32_e32 v116, v174, v116
	v_mul_f32_e32 v117, v175, v117
	v_cvt_pk_bf16_f32 v171, v116, v117
	s_waitcnt lgkmcnt(5)
	v_mfma_f32_16x16x32_bf16 v[40:43], v[176:179], v[168:171], v[40:43]
	s_waitcnt lgkmcnt(4)
	v_mfma_f32_16x16x32_bf16 v[44:47], v[180:183], v[168:171], v[44:47]
	s_waitcnt lgkmcnt(1)
	v_mfma_f32_16x16x32_bf16 v[48:51], v[184:187], v[168:171], v[48:51]
	s_waitcnt lgkmcnt(0)
	v_mfma_f32_16x16x32_bf16 v[52:55], v[188:191], v[168:171], v[52:55]
	ds_read_b128 v[168:171], v125 offset:256
	ds_read_b128 v[172:175], v125 offset:272
	ds_read_b64_tr_b16 v[116:117], v140 offset:9216
	ds_read_b64_tr_b16 v[192:193], v140 offset:9792
	ds_read_b64_tr_b16 v[176:177], v141 offset:52224
	ds_read_b64_tr_b16 v[180:181], v141 offset:52256
	ds_read_b64_tr_b16 v[178:179], v141 offset:53312
	ds_read_b64_tr_b16 v[182:183], v141 offset:53344
	ds_read_b64_tr_b16 v[184:185], v141 offset:52288
	ds_read_b64_tr_b16 v[188:189], v141 offset:52320
	ds_read_b64_tr_b16 v[186:187], v141 offset:53376
	ds_read_b64_tr_b16 v[190:191], v141 offset:53408
	s_waitcnt lgkmcnt(9)
	v_lshlrev_b32_e32 v194, 16, v116
	v_and_b32_e32 v116, 0xffff0000, v116
	v_mul_f32_e32 v168, v168, v194
	v_mul_f32_e32 v116, v169, v116
	v_cvt_pk_bf16_f32 v168, v168, v116
	v_lshlrev_b32_e32 v116, 16, v117
	v_and_b32_e32 v117, 0xffff0000, v117
	v_mul_f32_e32 v116, v170, v116
	v_mul_f32_e32 v117, v171, v117
	v_cvt_pk_bf16_f32 v169, v116, v117
	s_waitcnt lgkmcnt(8)
	v_lshlrev_b32_e32 v116, 16, v192
	v_and_b32_e32 v117, 0xffff0000, v192
	v_mul_f32_e32 v116, v172, v116
	v_mul_f32_e32 v117, v173, v117
	v_cvt_pk_bf16_f32 v170, v116, v117
	v_lshlrev_b32_e32 v116, 16, v193
	v_and_b32_e32 v117, 0xffff0000, v193
	v_mul_f32_e32 v116, v174, v116
	v_mul_f32_e32 v117, v175, v117
	v_cvt_pk_bf16_f32 v171, v116, v117
	s_waitcnt lgkmcnt(5)
	v_mfma_f32_16x16x32_bf16 v[40:43], v[176:179], v[168:171], v[40:43]
	s_waitcnt lgkmcnt(4)
	v_mfma_f32_16x16x32_bf16 v[44:47], v[180:183], v[168:171], v[44:47]
	s_waitcnt lgkmcnt(1)
	v_mfma_f32_16x16x32_bf16 v[48:51], v[184:187], v[168:171], v[48:51]
	s_waitcnt lgkmcnt(0)
	v_mfma_f32_16x16x32_bf16 v[52:55], v[188:191], v[168:171], v[52:55]
	ds_read_b128 v[168:171], v125 offset:384
	ds_read_b128 v[172:175], v125 offset:400
	ds_read_b64_tr_b16 v[116:117], v140 offset:13824
	ds_read_b64_tr_b16 v[192:193], v140 offset:14400
	ds_read_b64_tr_b16 v[176:177], v141 offset:60928
	ds_read_b64_tr_b16 v[180:181], v141 offset:60960
	ds_read_b64_tr_b16 v[178:179], v141 offset:62016
	ds_read_b64_tr_b16 v[182:183], v141 offset:62048
	ds_read_b64_tr_b16 v[184:185], v141 offset:60992
	ds_read_b64_tr_b16 v[188:189], v141 offset:61024
	ds_read_b64_tr_b16 v[186:187], v141 offset:62080
	ds_read_b64_tr_b16 v[190:191], v141 offset:62112
	s_waitcnt lgkmcnt(9)
	v_lshlrev_b32_e32 v194, 16, v116
	v_and_b32_e32 v116, 0xffff0000, v116
	v_mul_f32_e32 v168, v168, v194
	v_mul_f32_e32 v116, v169, v116
	v_cvt_pk_bf16_f32 v168, v168, v116
	v_lshlrev_b32_e32 v116, 16, v117
	v_and_b32_e32 v117, 0xffff0000, v117
	v_mul_f32_e32 v116, v170, v116
	v_mul_f32_e32 v117, v171, v117
	v_cvt_pk_bf16_f32 v169, v116, v117
	s_waitcnt lgkmcnt(8)
	v_lshlrev_b32_e32 v116, 16, v192
	v_and_b32_e32 v117, 0xffff0000, v192
	v_mul_f32_e32 v116, v172, v116
	v_mul_f32_e32 v117, v173, v117
	v_cvt_pk_bf16_f32 v170, v116, v117
	v_lshlrev_b32_e32 v116, 16, v193
	v_and_b32_e32 v117, 0xffff0000, v193
	v_mul_f32_e32 v116, v174, v116
	v_mul_f32_e32 v117, v175, v117
	v_cvt_pk_bf16_f32 v171, v116, v117
	s_waitcnt lgkmcnt(5)
	v_mfma_f32_16x16x32_bf16 v[40:43], v[176:179], v[168:171], v[40:43]
	s_waitcnt lgkmcnt(4)
	v_mfma_f32_16x16x32_bf16 v[44:47], v[180:183], v[168:171], v[44:47]
	s_waitcnt lgkmcnt(1)
	v_mfma_f32_16x16x32_bf16 v[48:51], v[184:187], v[168:171], v[48:51]
	s_waitcnt lgkmcnt(0)
	v_mfma_f32_16x16x32_bf16 v[52:55], v[188:191], v[168:171], v[52:55]

; #define LAS __attribute__((address_space(3)))
; __device__ __forceinline__ unsigned cvt_pk_bf16(float lo, float hi) { unsigned r; asm volatile("v_cvt_pk_bf16_f32 %0, %1, %2" : "=v"(r) : "v"(lo), "v"(hi)); return r; }
; #define MFMA16(a, b, c) __builtin_amdgcn_mfma_f32_16x16x32_bf16((a), (b), (c), 0, 0, 0)
; __device__ __forceinline__ void phase_C1(const Args& a, unsigned char* ws, const int bid, int l, LAS unsigned char* lds, int tid, int wave, int lane) {
;     ...
;               { const int k0 = qt * 16 + fq * 4; const f32x4 ck = *(const LAS f32x4*)(cs + k0), dk = *(const LAS f32x4*)(dtv + k0); float m[4];
; #pragma unroll
;                 for (int r = 0; r < 4; ++r) { const int kk = k0 + r; const bool keep = dir == 0 ? (kk <= q) : (kk >= q); m[r] = keep ? gd[r] * __expf(csq - ck[r]) * dk[r] : 0.f; }
;                 u32x2 o; o.x = cvt_pk_bf16(m[0], m[1]); o.y = cvt_pk_bf16(m[2], m[3]);
;                 *(LAS u32x2*)(L_M + q * 272 + k0 * 2) = o; }
;               f32x4 accB[4];
; #pragma unroll
;               for (int j = 0; j < 4; ++j) accB[j] = (f32x4){0.f, 0.f, 0.f, 0.f};
; #pragma unroll
;               for (int s = 0; s < 4; ++s) { const bf16x8 mq = *(const LAS bf16x8*)(L_M + qt * (16 * 272) + rb + s * 64);
;                   s16x4 xlo[4], xhi[4];
; #pragma unroll
;                   for (int pt = 0; pt < 4; ++pt) { xlo[pt] = __builtin_amdgcn_ds_read_tr16_b64_v4i16((LAS s16x4*)(L_X + trXp + (32 * s) * 144 + (32 * (pt >> 1) + 4 * (pt & 1)) * 2));
;                       xhi[pt] = __builtin_amdgcn_ds_read_tr16_b64_v4i16((LAS s16x4*)(L_X + trXp + (32 * s + 4) * 144 + (32 * (pt >> 1) + 4 * (pt & 1)) * 2)); }
;                   __builtin_amdgcn_sched_barrier(0);
; #pragma unroll
;                   for (int pt = 0; pt < 4; ++pt) { const bf16x8 xf = (bf16x8){xlo[pt].x, xlo[pt].y, xlo[pt].z, xlo[pt].w, xhi[pt].x, xhi[pt].y, xhi[pt].z, xhi[pt].w}; accB[pt] = MFMA16(xf, mq, accB[pt]); }
;                   __builtin_amdgcn_sched_barrier(0); }
.LBB0_123:
	s_or_b64 exec, exec, s[0:1]
	v_cndmask_b32_e64 v72, v170, v89, s[12:13]
	v_cndmask_b32_e64 v76, v169, v90, s[12:13]
	v_cndmask_b32_e64 v80, v168, v91, s[12:13]
	v_cndmask_b32_e64 v72, v72, v81, s[14:15]
	v_cndmask_b32_e64 v76, v76, v82, s[14:15]
	v_cndmask_b32_e64 v80, v80, v83, s[14:15]
	v_cndmask_b32_e64 v72, v72, v93, s[16:17]
	v_cndmask_b32_e64 v76, v76, v94, s[16:17]
	v_cndmask_b32_e64 v80, v80, v95, s[16:17]
	v_cndmask_b32_e64 v72, v72, v85, s[18:19]
	v_cndmask_b32_e64 v76, v76, v86, s[18:19]
	v_cndmask_b32_e64 v80, v80, v87, s[18:19]
	v_cndmask_b32_e64 v72, v72, v77, s[20:21]
	v_cndmask_b32_e64 v76, v76, v78, s[20:21]
	v_cndmask_b32_e64 v77, v80, v79, s[20:21]
	v_sub_f32_e32 v78, v117, v181
	v_cndmask_b32_e64 v72, v72, v73, s[22:23]
	v_cndmask_b32_e64 v73, v76, v74, s[22:23]
	v_cndmask_b32_e64 v74, v77, v75, s[22:23]
	v_sub_f32_e32 v75, v117, v182
	v_mul_f32_e32 v78, 0x3fb8aa3b, v78
	v_mul_f32_e32 v75, 0x3fb8aa3b, v75
	v_sub_f32_e32 v76, v117, v183
	v_exp_f32_e32 v78, v78
	v_exp_f32_e32 v75, v75
	v_mul_f32_e32 v76, 0x3fb8aa3b, v76
	v_exp_f32_e32 v76, v76
	v_mul_f32_e32 v72, v72, v78
	v_mul_f32_e32 v73, v73, v75
	v_mul_f32_e32 v72, v185, v72
	v_mul_f32_e32 v73, v186, v73
	v_mul_f32_e32 v74, v74, v76
	v_cndmask_b32_e64 v72, 0, v72, s[62:63]
	v_cndmask_b32_e64 v73, 0, v73, s[64:65]
	v_mul_f32_e32 v74, v187, v74
	v_cndmask_b32_e64 v74, 0, v74, s[66:67]
	v_cvt_pk_bf16_f32 v72, v172, v72
	v_cvt_pk_bf16_f32 v73, v73, v74
	ds_write_b64 v155, v[72:73]
	s_orn2_b64 vcc, s[46:47], s[70:71]
	s_or_b64 vcc, vcc, s[10:11]
	s_cbranch_vccz .Lssd_b_skip0
	ds_read_b128 v[72:75], v156
	ds_read_b64_tr_b16 v[76:77], v157
	ds_read_b64_tr_b16 v[78:79], v157 offset:576
	ds_read_b64_tr_b16 v[80:81], v157 offset:8
	ds_read_b64_tr_b16 v[84:85], v157 offset:64
	ds_read_b64_tr_b16 v[88:89], v157 offset:72
	ds_read_b64_tr_b16 v[82:83], v157 offset:584
	ds_read_b64_tr_b16 v[86:87], v157 offset:640
	ds_read_b64_tr_b16 v[90:91], v157 offset:648
	s_waitcnt lgkmcnt(6)
	v_mfma_f32_16x16x32_bf16 v[76:79], v[76:79], v[72:75], 0
	s_waitcnt lgkmcnt(2)
	v_mfma_f32_16x16x32_bf16 v[80:83], v[80:83], v[72:75], 0
	s_waitcnt lgkmcnt(1)
	v_mfma_f32_16x16x32_bf16 v[84:87], v[84:87], v[72:75], 0
	s_waitcnt lgkmcnt(0)
	v_mfma_f32_16x16x32_bf16 v[72:75], v[88:91], v[72:75], 0
	s_branch .Lssd_b_s1
.Lssd_b_skip0:
	v_mov_b32_e32 v72, 0
	v_mov_b32_e32 v73, 0
	v_mov_b32_e32 v74, 0
	v_mov_b32_e32 v75, 0
	v_mov_b32_e32 v76, 0
	v_mov_b32_e32 v77, 0
	v_mov_b32_e32 v78, 0
	v_mov_b32_e32 v79, 0
	v_mov_b32_e32 v80, 0
	v_mov_b32_e32 v81, 0
	v_mov_b32_e32 v82, 0
	v_mov_b32_e32 v83, 0
	v_mov_b32_e32 v84, 0
	v_mov_b32_e32 v85, 0
	v_mov_b32_e32 v86, 0
	v_mov_b32_e32 v87, 0
	s_nop 1
.Lssd_b_s1:
	s_or_b64 vcc, s[48:49], s[50:51]
	s_or_b64 vcc, vcc, s[12:13]
	s_or_b64 vcc, vcc, s[14:15]
	s_cbranch_vccz .Lssd_b_s2
	ds_read_b128 v[88:91], v156 offset:64
	ds_read_b64_tr_b16 v[92:93], v157 offset:4608
	ds_read_b64_tr_b16 v[94:95], v157 offset:5184
	ds_read_b64_tr_b16 v[96:97], v157 offset:4616
	ds_read_b64_tr_b16 v[100:101], v157 offset:4672
	ds_read_b64_tr_b16 v[168:169], v157 offset:4680
	ds_read_b64_tr_b16 v[98:99], v157 offset:5192
	ds_read_b64_tr_b16 v[102:103], v157 offset:5248
	ds_read_b64_tr_b16 v[170:171], v157 offset:5256
	s_waitcnt lgkmcnt(6)
	v_mfma_f32_16x16x32_bf16 v[76:79], v[92:95], v[88:91], v[76:79]
	s_waitcnt lgkmcnt(2)
	v_mfma_f32_16x16x32_bf16 v[80:83], v[96:99], v[88:91], v[80:83]
	s_waitcnt lgkmcnt(0)
	v_mfma_f32_16x16x32_bf16 v[72:75], v[168:171], v[88:91], v[72:75]
	v_mfma_f32_16x16x32_bf16 v[84:87], v[100:103], v[88:91], v[84:87]
.Lssd_b_s2:
	s_or_b64 vcc, s[52:53], s[54:55]
	s_or_b64 vcc, vcc, s[16:17]
	s_or_b64 vcc, vcc, s[18:19]
	s_cbranch_vccz .Lssd_b_s3
	ds_read_b128 v[88:91], v156 offset:128
	ds_read_b64_tr_b16 v[92:93], v157 offset:9216
	ds_read_b64_tr_b16 v[94:95], v157 offset:9792
	ds_read_b64_tr_b16 v[96:97], v157 offset:9224
	ds_read_b64_tr_b16 v[100:101], v157 offset:9280
	ds_read_b64_tr_b16 v[168:169], v157 offset:9288
	ds_read_b64_tr_b16 v[98:99], v157 offset:9800
	ds_read_b64_tr_b16 v[102:103], v157 offset:9856
	ds_read_b64_tr_b16 v[170:171], v157 offset:9864
	s_waitcnt lgkmcnt(6)
	v_mfma_f32_16x16x32_bf16 v[76:79], v[92:95], v[88:91], v[76:79]
	s_waitcnt lgkmcnt(2)
	v_mfma_f32_16x16x32_bf16 v[80:83], v[96:99], v[88:91], v[80:83]
	s_waitcnt lgkmcnt(0)
	v_mfma_f32_16x16x32_bf16 v[72:75], v[168:171], v[88:91], v[72:75]
	v_mfma_f32_16x16x32_bf16 v[84:87], v[100:103], v[88:91], v[84:87]
.Lssd_b_s3:
	s_or_b64 vcc, s[56:57], s[58:59]
	s_or_b64 vcc, vcc, s[20:21]
	s_or_b64 vcc, vcc, s[22:23]
	s_cbranch_vccz .Lssd_b_skip3
	ds_read_b128 v[88:91], v156 offset:192
	ds_read_b64_tr_b16 v[92:93], v157 offset:13824
	ds_read_b64_tr_b16 v[94:95], v157 offset:14400
	ds_read_b64_tr_b16 v[96:97], v157 offset:13832
	ds_read_b64_tr_b16 v[100:101], v157 offset:13888
	ds_read_b64_tr_b16 v[168:169], v157 offset:13896
	ds_read_b64_tr_b16 v[98:99], v157 offset:14408
	ds_read_b64_tr_b16 v[102:103], v157 offset:14464
	ds_read_b64_tr_b16 v[170:171], v157 offset:14472
	s_waitcnt lgkmcnt(6)
	v_mfma_f32_16x16x32_bf16 v[92:95], v[92:95], v[88:91], v[76:79]
	s_waitcnt lgkmcnt(1)
	v_mfma_f32_16x16x32_bf16 v[76:79], v[100:103], v[88:91], v[84:87]
	s_waitcnt lgkmcnt(0)
	v_mfma_f32_16x16x32_bf16 v[72:75], v[168:171], v[88:91], v[72:75]
	v_mfma_f32_16x16x32_bf16 v[96:99], v[96:99], v[88:91], v[80:83]
	s_branch .Lssd_b_done
.Lssd_b_skip3:
	s_nop 7
	s_nop 1
	v_mov_b32_e32 v92, v76
	v_mov_b32_e32 v93, v77
	v_mov_b32_e32 v94, v78
	v_mov_b32_e32 v95, v79
	v_mov_b32_e32 v96, v80
	v_mov_b32_e32 v97, v81
	v_mov_b32_e32 v98, v82
	v_mov_b32_e32 v99, v83
	v_mov_b32_e32 v76, v84
	v_mov_b32_e32 v77, v85
	v_mov_b32_e32 v78, v86
	v_mov_b32_e32 v79, v87
.Lssd_b_done:
	s_nop 2
	v_fma_f32 v80, v68, v116, v92
	v_fma_f32 v81, v69, v116, v93
	s_nop 2
	v_pk_fma_f32 v[68:69], v[64:65], v[116:117], v[96:97] op_sel_hi:[1,0,1]
	v_cndmask_b32_e64 v64, 0, 1, s[42:43]
	v_pk_fma_f32 v[70:71], v[70:71], v[116:117], v[94:95] op_sel_hi:[1,0,1]
	v_cmp_ne_u32_e64 s[0:1], 1, v64
	s_andn2_b64 vcc, exec, s[42:43]
	v_pk_fma_f32 v[66:67], v[66:67], v[116:117], v[98:99] op_sel_hi:[1,0,1]
	s_cbranch_vccnz .LBB0_125
	ds_read_b128 v[82:85], v165
	s_waitcnt lgkmcnt(0)
	v_lshlrev_b32_e32 v64, 16, v82
	v_and_b32_e32 v65, 0xffff0000, v82
	v_pk_fma_f32 v[80:81], v[110:111], v[64:65], v[80:81]
	v_lshlrev_b32_e32 v64, 16, v83
	v_and_b32_e32 v65, 0xffff0000, v83
	v_pk_fma_f32 v[70:71], v[110:111], v[64:65], v[70:71]
	v_lshlrev_b32_e32 v64, 16, v84
	v_and_b32_e32 v65, 0xffff0000, v84
	v_pk_fma_f32 v[68:69], v[110:111], v[64:65], v[68:69]
	v_lshlrev_b32_e32 v64, 16, v85
	v_and_b32_e32 v65, 0xffff0000, v85
	v_pk_fma_f32 v[66:67], v[110:111], v[64:65], v[66:67]

; #define LAS __attribute__((address_space(3)))
; __device__ __forceinline__ unsigned cvt_pk_bf16(float lo, float hi) { unsigned r; asm volatile("v_cvt_pk_bf16_f32 %0, %1, %2" : "=v"(r) : "v"(lo), "v"(hi)); return r; }
; #define MFMA16(a, b, c) __builtin_amdgcn_mfma_f32_16x16x32_bf16((a), (b), (c), 0, 0, 0)
; #define TRB(base, krow0, col0, t) __builtin_amdgcn_ds_read_tr16_b64_v4i16((LAS s16x4*)((base) + trB + ((krow0) + 4 * (t)) * 272 + (col0) * 2))
; #define TRX(base, krow0, col0, t) __builtin_amdgcn_ds_read_tr16_b64_v4i16((LAS s16x4*)((base) + trX + ((krow0) + 4 * (t)) * 144 + (col0) * 2))
; __device__ __forceinline__ void phase_C1(const Args& a, unsigned char* ws, const int bid, int l, LAS unsigned char* lds, int tid, int wave, int lane) {
;     ...
;             { const float etot = __expf(totp[0]);
; #pragma unroll
;               for (int j = 0; j < 4; ++j) Hacc[j] = Hacc[j] * etot;
; #pragma unroll
;               for (int s = 0; s < 4; ++s) { const s16x4 xlo = TRX(L_X, 32 * s, 16 * wr, 0), xhi = TRX(L_X, 32 * s, 16 * wr, 1);
;                   const f32x4 w0 = *(const LAS f32x4*)(wgt + s * 32 + fq * 8), w1 = *(const LAS f32x4*)(wgt + s * 32 + fq * 8 + 4);
;                   s16x4 blo[4], bhi[4];
; #pragma unroll
;                   for (int j = 0; j < 4; ++j) { blo[j] = TRB(L_B, 32 * s, 16 * (4 * wc + j), 0); bhi[j] = TRB(L_B, 32 * s, 16 * (4 * wc + j), 1); }
;                   __builtin_amdgcn_sched_barrier(0);
;                   const u32x2 xl = __builtin_bit_cast(u32x2, xlo), xh = __builtin_bit_cast(u32x2, xhi);
;                   u32x4 xs; xs.x = cvt_pk_bf16(bflo(xl.x) * w0.x, bfhi(xl.x) * w0.y); xs.y = cvt_pk_bf16(bflo(xl.y) * w0.z, bfhi(xl.y) * w0.w);
;                   xs.z = cvt_pk_bf16(bflo(xh.x) * w1.x, bfhi(xh.x) * w1.y); xs.w = cvt_pk_bf16(bflo(xh.y) * w1.z, bfhi(xh.y) * w1.w);
;                   const bf16x8 xq = __builtin_bit_cast(bf16x8, xs);
; #pragma unroll
;                   for (int j = 0; j < 4; ++j) { const bf16x8 bt = (bf16x8){blo[j].x, blo[j].y, blo[j].z, blo[j].w, bhi[j].x, bhi[j].y, bhi[j].z, bhi[j].w};
;                       Hacc[j] = MFMA16(bt, xq, Hacc[j]); }
;                   __builtin_amdgcn_sched_barrier(0); } }
.Lssd_alt_order:
	v_mov_b32_e32 v116, s87
	ds_read_b32 v116, v116
	s_waitcnt lgkmcnt(0)
	v_mul_f32_e32 v116, 0x3fb8aa3b, v116
	v_exp_f32_e32 v116, v116
	s_nop 0
	v_pk_mul_f32 v[42:43], v[42:43], v[116:117] op_sel_hi:[1,0]
	v_pk_mul_f32 v[40:41], v[40:41], v[116:117] op_sel_hi:[1,0]
	v_pk_mul_f32 v[46:47], v[46:47], v[116:117] op_sel_hi:[1,0]
	v_pk_mul_f32 v[44:45], v[44:45], v[116:117] op_sel_hi:[1,0]
	v_pk_mul_f32 v[50:51], v[50:51], v[116:117] op_sel_hi:[1,0]
	v_pk_mul_f32 v[48:49], v[48:49], v[116:117] op_sel_hi:[1,0]
	v_pk_mul_f32 v[54:55], v[54:55], v[116:117] op_sel_hi:[1,0]
	v_pk_mul_f32 v[52:53], v[52:53], v[116:117] op_sel_hi:[1,0]
	ds_read_b64_tr_b16 v[116:117], v140
	ds_read_b64_tr_b16 v[192:193], v140 offset:576
	ds_read_b128 v[168:171], v125
	ds_read_b128 v[172:175], v125 offset:16
	ds_read_b64_tr_b16 v[178:179], v141 offset:35904
	ds_read_b64_tr_b16 v[176:177], v141 offset:34816
	ds_read_b64_tr_b16 v[180:181], v141 offset:34848
	ds_read_b64_tr_b16 v[182:183], v141 offset:35936
	ds_read_b64_tr_b16 v[184:185], v141 offset:34880
	ds_read_b64_tr_b16 v[186:187], v141 offset:35968
	ds_read_b64_tr_b16 v[188:189], v141 offset:34912
	ds_read_b64_tr_b16 v[190:191], v141 offset:36000
	s_waitcnt lgkmcnt(11)
	v_lshlrev_b32_e32 v194, 16, v116
	v_and_b32_e32 v116, 0xffff0000, v116
	s_waitcnt lgkmcnt(9)
	v_mul_f32_e32 v168, v168, v194
	v_mul_f32_e32 v116, v169, v116
	v_cvt_pk_bf16_f32 v168, v168, v116
	v_lshlrev_b32_e32 v116, 16, v117
	v_and_b32_e32 v117, 0xffff0000, v117
	v_mul_f32_e32 v116, v170, v116
	v_mul_f32_e32 v117, v171, v117
	v_cvt_pk_bf16_f32 v169, v116, v117
	v_lshlrev_b32_e32 v116, 16, v192
	v_and_b32_e32 v117, 0xffff0000, v192
	s_waitcnt lgkmcnt(8)
	v_mul_f32_e32 v116, v172, v116
	v_mul_f32_e32 v117, v173, v117
	v_cvt_pk_bf16_f32 v170, v116, v117
	v_lshlrev_b32_e32 v116, 16, v193
	v_and_b32_e32 v117, 0xffff0000, v193
	v_mul_f32_e32 v116, v174, v116
	v_mul_f32_e32 v117, v175, v117
	v_cvt_pk_bf16_f32 v171, v116, v117
	s_waitcnt lgkmcnt(6)
	v_mfma_f32_16x16x32_bf16 v[40:43], v[176:179], v[168:171], v[40:43]
	s_waitcnt lgkmcnt(4)
	v_mfma_f32_16x16x32_bf16 v[44:47], v[180:183], v[168:171], v[44:47]
	s_waitcnt lgkmcnt(2)
	v_mfma_f32_16x16x32_bf16 v[48:51], v[184:187], v[168:171], v[48:51]
	s_waitcnt lgkmcnt(0)
	v_mfma_f32_16x16x32_bf16 v[52:55], v[188:191], v[168:171], v[52:55]
	ds_read_b128 v[168:171], v125 offset:128
	ds_read_b128 v[172:175], v125 offset:144
	ds_read_b64_tr_b16 v[116:117], v140 offset:4608
	ds_read_b64_tr_b16 v[192:193], v140 offset:5184
	ds_read_b64_tr_b16 v[176:177], v141 offset:43520
	ds_read_b64_tr_b16 v[180:181], v141 offset:43552
	ds_read_b64_tr_b16 v[178:179], v141 offset:44608
	ds_read_b64_tr_b16 v[182:183], v141 offset:44640
	ds_read_b64_tr_b16 v[184:185], v141 offset:43584
	ds_read_b64_tr_b16 v[188:189], v141 offset:43616
	ds_read_b64_tr_b16 v[186:187], v141 offset:44672
	ds_read_b64_tr_b16 v[190:191], v141 offset:44704
	s_waitcnt lgkmcnt(9)
	v_lshlrev_b32_e32 v194, 16, v116
	v_and_b32_e32 v116, 0xffff0000, v116
	v_mul_f32_e32 v168, v168, v194
	v_mul_f32_e32 v116, v169, v116
	v_cvt_pk_bf16_f32 v168, v168, v116
	v_lshlrev_b32_e32 v116, 16, v117
	v_and_b32_e32 v117, 0xffff0000, v117
	v_mul_f32_e32 v116, v170, v116
	v_mul_f32_e32 v117, v171, v117
	v_cvt_pk_bf16_f32 v169, v116, v117
	s_waitcnt lgkmcnt(8)
	v_lshlrev_b32_e32 v116, 16, v192
	v_and_b32_e32 v117, 0xffff0000, v192
	v_mul_f32_e32 v116, v172, v116
	v_mul_f32_e32 v117, v173, v117
	v_cvt_pk_bf16_f32 v170, v116, v117
	v_lshlrev_b32_e32 v116, 16, v193
	v_and_b32_e32 v117, 0xffff0000, v193
	v_mul_f32_e32 v116, v174, v116
	v_mul_f32_e32 v117, v175, v117
	v_cvt_pk_bf16_f32 v171, v116, v117
	s_waitcnt lgkmcnt(5)
	v_mfma_f32_16x16x32_bf16 v[40:43], v[176:179], v[168:171], v[40:43]
	s_waitcnt lgkmcnt(4)
	v_mfma_f32_16x16x32_bf16 v[44:47], v[180:183], v[168:171], v[44:47]
	s_waitcnt lgkmcnt(1)
	v_mfma_f32_16x16x32_bf16 v[48:51], v[184:187], v[168:171], v[48:51]
	s_waitcnt lgkmcnt(0)
	v_mfma_f32_16x16x32_bf16 v[52:55], v[188:191], v[168:171], v[52:55]
	ds_read_b128 v[168:171], v125 offset:256
	ds_read_b128 v[172:175], v125 offset:272
	ds_read_b64_tr_b16 v[116:117], v140 offset:9216
	ds_read_b64_tr_b16 v[192:193], v140 offset:9792
	ds_read_b64_tr_b16 v[176:177], v141 offset:52224
	ds_read_b64_tr_b16 v[180:181], v141 offset:52256
	ds_read_b64_tr_b16 v[178:179], v141 offset:53312
	ds_read_b64_tr_b16 v[182:183], v141 offset:53344
	ds_read_b64_tr_b16 v[184:185], v141 offset:52288
	ds_read_b64_tr_b16 v[188:189], v141 offset:52320
	ds_read_b64_tr_b16 v[186:187], v141 offset:53376
	ds_read_b64_tr_b16 v[190:191], v141 offset:53408
	s_waitcnt lgkmcnt(9)
	v_lshlrev_b32_e32 v194, 16, v116
	v_and_b32_e32 v116, 0xffff0000, v116
	v_mul_f32_e32 v168, v168, v194
	v_mul_f32_e32 v116, v169, v116
	v_cvt_pk_bf16_f32 v168, v168, v116
	v_lshlrev_b32_e32 v116, 16, v117
	v_and_b32_e32 v117, 0xffff0000, v117
	v_mul_f32_e32 v116, v170, v116
	v_mul_f32_e32 v117, v171, v117
	v_cvt_pk_bf16_f32 v169, v116, v117
	s_waitcnt lgkmcnt(8)
	v_lshlrev_b32_e32 v116, 16, v192
	v_and_b32_e32 v117, 0xffff0000, v192
	v_mul_f32_e32 v116, v172, v116
	v_mul_f32_e32 v117, v173, v117
	v_cvt_pk_bf16_f32 v170, v116, v117
	v_lshlrev_b32_e32 v116, 16, v193
	v_and_b32_e32 v117, 0xffff0000, v193
	v_mul_f32_e32 v116, v174, v116
	v_mul_f32_e32 v117, v175, v117
	v_cvt_pk_bf16_f32 v171, v116, v117
	s_waitcnt lgkmcnt(5)
	v_mfma_f32_16x16x32_bf16 v[40:43], v[176:179], v[168:171], v[40:43]
	s_waitcnt lgkmcnt(4)
	v_mfma_f32_16x16x32_bf16 v[44:47], v[180:183], v[168:171], v[44:47]
	s_waitcnt lgkmcnt(1)
	v_mfma_f32_16x16x32_bf16 v[48:51], v[184:187], v[168:171], v[48:51]
	s_waitcnt lgkmcnt(0)
; #define LAS __attribute__((address_space(3)))
; __device__ __forceinline__ unsigned cvt_pk_bf16(float lo, float hi) { unsigned r; asm volatile("v_cvt_pk_bf16_f32 %0, %1, %2" : "=v"(r) : "v"(lo), "v"(hi)); return r; }
; __device__ __forceinline__ void phase_C1(const Args& a, unsigned char* ws, const int bid, int l, LAS unsigned char* lds, int tid, int wave, int lane) {
;     ...
;             {
;                 bf16x8 cqv[2], bq[2][4], hq[2][2];
;     ...
;                 SSD_LDH(0, 0);
; #pragma unroll
;                 for (int h2 = 0; h2 < 8; ++h2) { const int cb = h2 & 1, s_ = h2 >> 1, hf_ = h2 & 1;
;                     if (h2 < 7) SSD_LDH(cb ^ 1, h2 + 1);
;                     __builtin_amdgcn_sched_barrier(0);
; #pragma unroll
;                     for (int k = 0; k < 4; ++k) accA[4 * hf_ + k] = MFMA16(bq[cb][k], cqv[s_ & 1], accA[4 * hf_ + k]);
; #pragma unroll
;                     for (int p = 0; p < 2; ++p) accC[2 * hf_ + p] = MFMA16(hq[cb][p], cqv[s_ & 1], accC[2 * hf_ + p]);
;                     __builtin_amdgcn_sched_barrier(0); }
;     ...
;               for (int s = 0; s < 4; ++s) { const s16x4 xlo = TRX(L_X, 32 * s, 16 * wr, 0), xhi = TRX(L_X, 32 * s, 16 * wr, 1);
;                   const f32x4 w0 = *(const LAS f32x4*)(wgt + s * 32 + fq * 8), w1 = *(const LAS f32x4*)(wgt + s * 32 + fq * 8 + 4);
;                   s16x4 blo[4], bhi[4];
; #pragma unroll
;                   for (int j = 0; j < 4; ++j) { blo[j] = TRB(L_B, 32 * s, 16 * (4 * wc + j), 0); bhi[j] = TRB(L_B, 32 * s, 16 * (4 * wc + j), 1); }
;                   __builtin_amdgcn_sched_barrier(0);
;                   const u32x2 xl = __builtin_bit_cast(u32x2, xlo), xh = __builtin_bit_cast(u32x2, xhi);
;                   u32x4 xs; xs.x = cvt_pk_bf16(bflo(xl.x) * w0.x, bfhi(xl.x) * w0.y); xs.y = cvt_pk_bf16(bflo(xl.y) * w0.z, bfhi(xl.y) * w0.w);
;                   xs.z = cvt_pk_bf16(bflo(xh.x) * w1.x, bfhi(xh.x) * w1.y); xs.w = cvt_pk_bf16(bflo(xh.y) * w1.z, bfhi(xh.y) * w1.w);
;                   const bf16x8 xq = __builtin_bit_cast(bf16x8, xs);
; #pragma unroll
;                   for (int j = 0; j < 4; ++j) { const bf16x8 bt = (bf16x8){blo[j].x, blo[j].y, blo[j].z, blo[j].w, bhi[j].x, bhi[j].y, bhi[j].z, bhi[j].w};
;                       Hacc[j] = MFMA16(bt, xq, Hacc[j]); }
;                   __builtin_amdgcn_sched_barrier(0); } }
	v_mfma_f32_16x16x32_bf16 v[52:55], v[188:191], v[168:171], v[52:55]
	ds_read_b128 v[168:171], v125 offset:384
	ds_read_b128 v[172:175], v125 offset:400
	ds_read_b64_tr_b16 v[116:117], v140 offset:13824
	ds_read_b64_tr_b16 v[192:193], v140 offset:14400
	ds_read_b64_tr_b16 v[176:177], v141 offset:60928
	ds_read_b64_tr_b16 v[180:181], v141 offset:60960
	ds_read_b64_tr_b16 v[178:179], v141 offset:62016
	ds_read_b64_tr_b16 v[182:183], v141 offset:62048
	ds_read_b64_tr_b16 v[184:185], v141 offset:60992
	ds_read_b64_tr_b16 v[188:189], v141 offset:61024
	ds_read_b64_tr_b16 v[186:187], v141 offset:62080
	ds_read_b64_tr_b16 v[190:191], v141 offset:62112
	s_waitcnt lgkmcnt(9)
	v_lshlrev_b32_e32 v194, 16, v116
	v_and_b32_e32 v116, 0xffff0000, v116
	v_mul_f32_e32 v168, v168, v194
	v_mul_f32_e32 v116, v169, v116
	v_cvt_pk_bf16_f32 v168, v168, v116
	v_lshlrev_b32_e32 v116, 16, v117
	v_and_b32_e32 v117, 0xffff0000, v117
	v_mul_f32_e32 v116, v170, v116
	v_mul_f32_e32 v117, v171, v117
	v_cvt_pk_bf16_f32 v169, v116, v117
	s_waitcnt lgkmcnt(8)
	v_lshlrev_b32_e32 v116, 16, v192
	v_and_b32_e32 v117, 0xffff0000, v192
	v_mul_f32_e32 v116, v172, v116
	v_mul_f32_e32 v117, v173, v117
	v_cvt_pk_bf16_f32 v170, v116, v117
	v_lshlrev_b32_e32 v116, 16, v193
	v_and_b32_e32 v117, 0xffff0000, v193
	v_mul_f32_e32 v116, v174, v116
	v_mul_f32_e32 v117, v175, v117
	v_cvt_pk_bf16_f32 v171, v116, v117
	s_waitcnt lgkmcnt(5)
	v_mfma_f32_16x16x32_bf16 v[40:43], v[176:179], v[168:171], v[40:43]
	s_waitcnt lgkmcnt(4)
	v_mfma_f32_16x16x32_bf16 v[44:47], v[180:183], v[168:171], v[44:47]
	s_waitcnt lgkmcnt(1)
	v_mfma_f32_16x16x32_bf16 v[48:51], v[184:187], v[168:171], v[48:51]
	s_waitcnt lgkmcnt(0)
	v_mfma_f32_16x16x32_bf16 v[52:55], v[188:191], v[168:171], v[52:55]
	s_branch .Lssd_A_dispatch
.Lssd_A_ret_alt:
	v_mov_b32_e32 v116, 0x22e00
	ds_read_b128 v[244:247], v116
	ds_read_b128 v[248:251], v116 offset:16
	ds_read_b128 v[216:219], v133
	ds_read_b128 v[220:223], v134
	ds_read_b128 v[224:227], v135
	ds_read_b128 v[228:231], v136
	ds_read_b128 v[232:235], v137
	ds_read_b128 v[236:239], v138
	ds_read_b128 v[240:243], v139
	ds_read_b128 v[212:215], v132
	s_branch .Lssd_m_section
.Lssd_A_dispatch:
	s_orn2_b64 vcc, s[46:47], s[70:71]
	s_or_b64 vcc, vcc, s[10:11]
	s_cbranch_vccz .Lssd_A_n0_0
	s_or_b64 vcc, s[48:49], s[50:51]
	s_or_b64 vcc, vcc, s[12:13]
	s_or_b64 vcc, vcc, s[14:15]
	s_cbranch_vccz .Lssd_A_1000
	s_or_b64 vcc, s[52:53], s[54:55]
	s_or_b64 vcc, vcc, s[16:17]
	s_or_b64 vcc, vcc, s[18:19]
	s_cbranch_vccz .Lssd_A_1100
	s_or_b64 vcc, s[56:57], s[58:59]
	s_or_b64 vcc, vcc, s[20:21]
	s_or_b64 vcc, vcc, s[22:23]
	s_cbranch_vccz .Lssd_A_1110
	s_branch .Lssd_A_1111
.Lssd_A_n0_0:
	s_or_b64 vcc, s[48:49], s[50:51]
	s_or_b64 vcc, vcc, s[12:13]
	s_or_b64 vcc, vcc, s[14:15]
	s_cbranch_vccnz .Lssd_A_0111
	s_or_b64 vcc, s[52:53], s[54:55]
	s_or_b64 vcc, vcc, s[16:17]
	s_or_b64 vcc, vcc, s[18:19]
	s_cbranch_vccnz .Lssd_A_0011
	s_branch .Lssd_A_0001
.Lssd_A_1111:
	v_add_u32_e32 v116, s33, v118
	ds_read_b128 v[56:59], v118 offset:34816
	ds_read_b128 v[60:63], v118 offset:39168
	ds_read_b128 v[64:67], v118 offset:43520
	ds_read_b128 v[68:71], v118 offset:47872
	ds_read_b128 v[72:75], v116
	ds_read_b128 v[76:79], v147
	ds_read_b128 v[80:83], v118 offset:52224
	ds_read_b128 v[84:87], v118 offset:56576
	ds_read_b128 v[88:91], v118 offset:60928
	ds_read_b128 v[92:95], v118 offset:65280
	ds_read_b128 v[96:99], v147 offset:1088
	ds_read_b128 v[100:103], v147 offset:8704
	ds_read_b128 v[168:171], v147 offset:9792
	s_waitcnt lgkmcnt(8)
	v_mfma_f32_16x16x32_bf16 v[56:59], v[56:59], v[72:75], 0
	v_mfma_f32_16x16x32_bf16 v[60:63], v[60:63], v[72:75], 0
	v_mfma_f32_16x16x32_bf16 v[64:67], v[64:67], v[72:75], 0
	v_mfma_f32_16x16x32_bf16 v[68:71], v[68:71], v[72:75], 0
	s_waitcnt lgkmcnt(7)
	v_mfma_f32_16x16x32_bf16 v[76:79], v[76:79], v[72:75], 0
	s_waitcnt lgkmcnt(2)
	v_mfma_f32_16x16x32_bf16 v[96:99], v[96:99], v[72:75], 0
	ds_read_b128 v[172:175], v118 offset:34880
	ds_read_b128 v[176:179], v118 offset:39232
	ds_read_b128 v[180:183], v118 offset:43584
	ds_read_b128 v[184:187], v118 offset:47936
	ds_read_b128 v[188:191], v116 offset:64
	ds_read_b128 v[212:215], v147 offset:64
	ds_read_b128 v[216:219], v147 offset:1152
	v_mfma_f32_16x16x32_bf16 v[80:83], v[80:83], v[72:75], 0
	v_mfma_f32_16x16x32_bf16 v[84:87], v[84:87], v[72:75], 0
	v_mfma_f32_16x16x32_bf16 v[88:91], v[88:91], v[72:75], 0
	v_mfma_f32_16x16x32_bf16 v[92:95], v[92:95], v[72:75], 0
	s_waitcnt lgkmcnt(8)
	v_mfma_f32_16x16x32_bf16 v[100:103], v[100:103], v[72:75], 0
	s_waitcnt lgkmcnt(7)
	v_mfma_f32_16x16x32_bf16 v[72:75], v[168:171], v[72:75], 0
	ds_read_b128 v[168:171], v118 offset:52288
	ds_read_b128 v[220:223], v118 offset:56640
	ds_read_b128 v[224:227], v118 offset:60992
	ds_read_b128 v[228:231], v118 offset:65344
	ds_read_b128 v[232:235], v147 offset:8768
	ds_read_b128 v[236:239], v147 offset:9856
	s_waitcnt lgkmcnt(8)
	v_mfma_f32_16x16x32_bf16 v[56:59], v[172:175], v[188:191], v[56:59]
	v_mfma_f32_16x16x32_bf16 v[60:63], v[176:179], v[188:191], v[60:63]
	v_mfma_f32_16x16x32_bf16 v[64:67], v[180:183], v[188:191], v[64:67]
	v_mfma_f32_16x16x32_bf16 v[68:71], v[184:187], v[188:191], v[68:71]
	s_waitcnt lgkmcnt(7)
	v_mfma_f32_16x16x32_bf16 v[76:79], v[212:215], v[188:191], v[76:79]
	s_waitcnt lgkmcnt(6)
	v_mfma_f32_16x16x32_bf16 v[96:99], v[216:219], v[188:191], v[96:99]
	ds_read_b128 v[172:175], v118 offset:34944
	ds_read_b128 v[176:179], v118 offset:39296
	ds_read_b128 v[180:183], v118 offset:43648
	ds_read_b128 v[184:187], v118 offset:48000
	ds_read_b128 v[212:215], v116 offset:128
	ds_read_b128 v[216:219], v147 offset:128
	ds_read_b128 v[240:243], v147 offset:1216
	s_waitcnt lgkmcnt(12)
; #define MFMA16(a, b, c) __builtin_amdgcn_mfma_f32_16x16x32_bf16((a), (b), (c), 0, 0, 0)
; __device__ __forceinline__ void phase_C1(const Args& a, unsigned char* ws, const int bid, int l, LAS unsigned char* lds, int tid, int wave, int lane) {
;     ...
;             {
;                 bf16x8 cqv[2], bq[2][4], hq[2][2];
;     ...
;                 SSD_LDH(0, 0);
; #pragma unroll
;                 for (int h2 = 0; h2 < 8; ++h2) { const int cb = h2 & 1, s_ = h2 >> 1, hf_ = h2 & 1;
;                     if (h2 < 7) SSD_LDH(cb ^ 1, h2 + 1);
;                     __builtin_amdgcn_sched_barrier(0);
; #pragma unroll
;                     for (int k = 0; k < 4; ++k) accA[4 * hf_ + k] = MFMA16(bq[cb][k], cqv[s_ & 1], accA[4 * hf_ + k]);
; #pragma unroll
;                     for (int p = 0; p < 2; ++p) accC[2 * hf_ + p] = MFMA16(hq[cb][p], cqv[s_ & 1], accC[2 * hf_ + p]);
;                     __builtin_amdgcn_sched_barrier(0); }
	v_mfma_f32_16x16x32_bf16 v[80:83], v[168:171], v[188:191], v[80:83]
	s_waitcnt lgkmcnt(11)
	v_mfma_f32_16x16x32_bf16 v[84:87], v[220:223], v[188:191], v[84:87]
	s_waitcnt lgkmcnt(10)
	v_mfma_f32_16x16x32_bf16 v[88:91], v[224:227], v[188:191], v[88:91]
	s_waitcnt lgkmcnt(9)
	v_mfma_f32_16x16x32_bf16 v[92:95], v[228:231], v[188:191], v[92:95]
	s_waitcnt lgkmcnt(8)
	v_mfma_f32_16x16x32_bf16 v[100:103], v[232:235], v[188:191], v[100:103]
	s_waitcnt lgkmcnt(7)
	v_mfma_f32_16x16x32_bf16 v[72:75], v[236:239], v[188:191], v[72:75]
	ds_read_b128 v[168:171], v118 offset:52352
	ds_read_b128 v[188:191], v118 offset:56704
	ds_read_b128 v[220:223], v118 offset:61056
	ds_read_b128 v[224:227], v118 offset:65408
	ds_read_b128 v[228:231], v147 offset:8832
	ds_read_b128 v[232:235], v147 offset:9920
	s_waitcnt lgkmcnt(8)
	v_mfma_f32_16x16x32_bf16 v[56:59], v[172:175], v[212:215], v[56:59]
	v_mfma_f32_16x16x32_bf16 v[60:63], v[176:179], v[212:215], v[60:63]
	v_mfma_f32_16x16x32_bf16 v[64:67], v[180:183], v[212:215], v[64:67]
	v_mfma_f32_16x16x32_bf16 v[68:71], v[184:187], v[212:215], v[68:71]
	s_waitcnt lgkmcnt(7)
	v_mfma_f32_16x16x32_bf16 v[76:79], v[216:219], v[212:215], v[76:79]
	s_waitcnt lgkmcnt(6)
	v_mfma_f32_16x16x32_bf16 v[172:175], v[240:243], v[212:215], v[96:99]
	s_nop 2
	ds_read_b128 v[96:99], v118 offset:35008
	ds_read_b128 v[176:179], v118 offset:39360
	ds_read_b128 v[180:183], v118 offset:43712
	ds_read_b128 v[184:187], v118 offset:48064
	ds_read_b128 v[216:219], v116 offset:192
	ds_read_b128 v[236:239], v147 offset:192
	ds_read_b128 v[240:243], v147 offset:1280
	s_waitcnt lgkmcnt(12)
	v_mfma_f32_16x16x32_bf16 v[168:171], v[168:171], v[212:215], v[80:83]
	s_waitcnt lgkmcnt(11)
	v_mfma_f32_16x16x32_bf16 v[84:87], v[188:191], v[212:215], v[84:87]
	s_waitcnt lgkmcnt(10)
	v_mfma_f32_16x16x32_bf16 v[188:191], v[220:223], v[212:215], v[88:91]
	s_waitcnt lgkmcnt(9)
	v_mfma_f32_16x16x32_bf16 v[220:223], v[224:227], v[212:215], v[92:95]
	s_waitcnt lgkmcnt(8)
	v_mfma_f32_16x16x32_bf16 v[224:227], v[228:231], v[212:215], v[100:103]
	s_waitcnt lgkmcnt(7)
	v_mfma_f32_16x16x32_bf16 v[212:215], v[232:235], v[212:215], v[72:75]
	s_nop 2
	ds_read_b128 v[72:75], v118 offset:52416
	ds_read_b128 v[228:231], v118 offset:56768
	ds_read_b128 v[232:235], v118 offset:61120
	ds_read_b128 v[244:247], v118 offset:65472
	ds_read_b128 v[248:251], v147 offset:8896
	ds_read_b128 v[192:195], v147 offset:9984
	s_waitcnt lgkmcnt(8)
	v_mfma_f32_16x16x32_bf16 v[100:103], v[96:99], v[216:219], v[56:59]
	v_mfma_f32_16x16x32_bf16 v[96:99], v[176:179], v[216:219], v[60:63]
	v_mfma_f32_16x16x32_bf16 v[88:91], v[180:183], v[216:219], v[64:67]
	v_mfma_f32_16x16x32_bf16 v[80:83], v[184:187], v[216:219], v[68:71]
	s_waitcnt lgkmcnt(7)
	v_mfma_f32_16x16x32_bf16 v[68:71], v[236:239], v[216:219], v[76:79]
	s_waitcnt lgkmcnt(6)
	v_mfma_f32_16x16x32_bf16 v[64:67], v[240:243], v[216:219], v[172:175]
	s_waitcnt lgkmcnt(5)
	v_mfma_f32_16x16x32_bf16 v[92:95], v[72:75], v[216:219], v[168:171]
	s_waitcnt lgkmcnt(4)
	v_mfma_f32_16x16x32_bf16 v[84:87], v[228:231], v[216:219], v[84:87]
	s_waitcnt lgkmcnt(3)
	v_mfma_f32_16x16x32_bf16 v[76:79], v[232:235], v[216:219], v[188:191]
	s_waitcnt lgkmcnt(2)
	v_mfma_f32_16x16x32_bf16 v[72:75], v[244:247], v[216:219], v[220:223]
	s_waitcnt lgkmcnt(1)
	v_mfma_f32_16x16x32_bf16 v[60:63], v[248:251], v[216:219], v[224:227]
	s_waitcnt lgkmcnt(0)
	v_mfma_f32_16x16x32_bf16 v[56:59], v[192:195], v[216:219], v[212:215]
	s_branch .Lssd_A_join
.Lssd_A_1000:
	v_add_u32_e32 v116, s33, v118
	ds_read_b128 v[56:59], v118 offset:34816
	ds_read_b128 v[60:63], v118 offset:39168
	ds_read_b128 v[72:75], v116
	ds_read_b128 v[76:79], v147
	ds_read_b128 v[96:99], v147 offset:1088
	ds_read_b128 v[100:103], v147 offset:8704
	ds_read_b128 v[168:171], v147 offset:9792
	s_waitcnt lgkmcnt(4)
	v_mfma_f32_16x16x32_bf16 v[56:59], v[56:59], v[72:75], 0
	v_mfma_f32_16x16x32_bf16 v[60:63], v[60:63], v[72:75], 0
	s_waitcnt lgkmcnt(3)
	v_mfma_f32_16x16x32_bf16 v[76:79], v[76:79], v[72:75], 0
	s_waitcnt lgkmcnt(2)
	v_mfma_f32_16x16x32_bf16 v[96:99], v[96:99], v[72:75], 0
	ds_read_b128 v[172:175], v118 offset:34880
	ds_read_b128 v[176:179], v118 offset:39232
	ds_read_b128 v[188:191], v116 offset:64
	ds_read_b128 v[212:215], v147 offset:64
	ds_read_b128 v[216:219], v147 offset:1152
	s_waitcnt lgkmcnt(6)
	v_mfma_f32_16x16x32_bf16 v[100:103], v[100:103], v[72:75], 0
	s_waitcnt lgkmcnt(5)
	v_mfma_f32_16x16x32_bf16 v[72:75], v[168:171], v[72:75], 0
	ds_read_b128 v[232:235], v147 offset:8768
	ds_read_b128 v[236:239], v147 offset:9856
	s_waitcnt lgkmcnt(4)
	v_mfma_f32_16x16x32_bf16 v[56:59], v[172:175], v[188:191], v[56:59]
	v_mfma_f32_16x16x32_bf16 v[60:63], v[176:179], v[188:191], v[60:63]
	s_waitcnt lgkmcnt(3)
	v_mfma_f32_16x16x32_bf16 v[76:79], v[212:215], v[188:191], v[76:79]
	s_waitcnt lgkmcnt(2)
	v_mfma_f32_16x16x32_bf16 v[96:99], v[216:219], v[188:191], v[96:99]
	ds_read_b128 v[172:175], v118 offset:34944
	ds_read_b128 v[176:179], v118 offset:39296
	ds_read_b128 v[212:215], v116 offset:128
	ds_read_b128 v[216:219], v147 offset:128
	ds_read_b128 v[240:243], v147 offset:1216
	s_waitcnt lgkmcnt(6)
	v_mfma_f32_16x16x32_bf16 v[100:103], v[232:235], v[188:191], v[100:103]
	s_waitcnt lgkmcnt(5)
	v_mfma_f32_16x16x32_bf16 v[72:75], v[236:239], v[188:191], v[72:75]
	ds_read_b128 v[228:231], v147 offset:8832
	ds_read_b128 v[232:235], v147 offset:9920
	s_waitcnt lgkmcnt(4)
	v_mfma_f32_16x16x32_bf16 v[56:59], v[172:175], v[212:215], v[56:59]
	v_mfma_f32_16x16x32_bf16 v[60:63], v[176:179], v[212:215], v[60:63]
	s_waitcnt lgkmcnt(3)
	v_mfma_f32_16x16x32_bf16 v[76:79], v[216:219], v[212:215], v[76:79]
	s_waitcnt lgkmcnt(2)
	v_mfma_f32_16x16x32_bf16 v[172:175], v[240:243], v[212:215], v[96:99]
	s_nop 2
	ds_read_b128 v[96:99], v118 offset:35008
	ds_read_b128 v[176:179], v118 offset:39360
	ds_read_b128 v[216:219], v116 offset:192
	ds_read_b128 v[236:239], v147 offset:192
	ds_read_b128 v[240:243], v147 offset:1280
	s_waitcnt lgkmcnt(6)
	v_mfma_f32_16x16x32_bf16 v[224:227], v[228:231], v[212:215], v[100:103]
	s_waitcnt lgkmcnt(5)
	v_mfma_f32_16x16x32_bf16 v[212:215], v[232:235], v[212:215], v[72:75]
	s_nop 2
	ds_read_b128 v[248:251], v147 offset:8896
	ds_read_b128 v[192:195], v147 offset:9984
	s_waitcnt lgkmcnt(4)
	v_mfma_f32_16x16x32_bf16 v[100:103], v[96:99], v[216:219], v[56:59]
	v_mfma_f32_16x16x32_bf16 v[96:99], v[176:179], v[216:219], v[60:63]
	s_waitcnt lgkmcnt(3)
	v_mfma_f32_16x16x32_bf16 v[68:71], v[236:239], v[216:219], v[76:79]
	s_waitcnt lgkmcnt(2)
	v_mfma_f32_16x16x32_bf16 v[64:67], v[240:243], v[216:219], v[172:175]
	s_waitcnt lgkmcnt(1)
	v_mfma_f32_16x16x32_bf16 v[60:63], v[248:251], v[216:219], v[224:227]
	s_waitcnt lgkmcnt(0)
	v_mfma_f32_16x16x32_bf16 v[56:59], v[192:195], v[216:219], v[212:215]
	s_branch .Lssd_A_join
; #define MFMA16(a, b, c) __builtin_amdgcn_mfma_f32_16x16x32_bf16((a), (b), (c), 0, 0, 0)
; __device__ __forceinline__ void phase_C1(const Args& a, unsigned char* ws, const int bid, int l, LAS unsigned char* lds, int tid, int wave, int lane) {
;     ...
;             {
;                 bf16x8 cqv[2], bq[2][4], hq[2][2];
;     ...
;                 SSD_LDH(0, 0);
; #pragma unroll
;                 for (int h2 = 0; h2 < 8; ++h2) { const int cb = h2 & 1, s_ = h2 >> 1, hf_ = h2 & 1;
;                     if (h2 < 7) SSD_LDH(cb ^ 1, h2 + 1);
;                     __builtin_amdgcn_sched_barrier(0);
; #pragma unroll
;                     for (int k = 0; k < 4; ++k) accA[4 * hf_ + k] = MFMA16(bq[cb][k], cqv[s_ & 1], accA[4 * hf_ + k]);
; #pragma unroll
;                     for (int p = 0; p < 2; ++p) accC[2 * hf_ + p] = MFMA16(hq[cb][p], cqv[s_ & 1], accC[2 * hf_ + p]);
;                     __builtin_amdgcn_sched_barrier(0); }
.Lssd_A_1100:
	v_add_u32_e32 v116, s33, v118
	ds_read_b128 v[56:59], v118 offset:34816
	ds_read_b128 v[60:63], v118 offset:39168
	ds_read_b128 v[64:67], v118 offset:43520
	ds_read_b128 v[68:71], v118 offset:47872
	ds_read_b128 v[72:75], v116
	ds_read_b128 v[76:79], v147
	ds_read_b128 v[96:99], v147 offset:1088
	ds_read_b128 v[100:103], v147 offset:8704
	ds_read_b128 v[168:171], v147 offset:9792
	s_waitcnt lgkmcnt(4)
	v_mfma_f32_16x16x32_bf16 v[56:59], v[56:59], v[72:75], 0
	v_mfma_f32_16x16x32_bf16 v[60:63], v[60:63], v[72:75], 0
	v_mfma_f32_16x16x32_bf16 v[64:67], v[64:67], v[72:75], 0
	v_mfma_f32_16x16x32_bf16 v[68:71], v[68:71], v[72:75], 0
	s_waitcnt lgkmcnt(3)
	v_mfma_f32_16x16x32_bf16 v[76:79], v[76:79], v[72:75], 0
	s_waitcnt lgkmcnt(2)
	v_mfma_f32_16x16x32_bf16 v[96:99], v[96:99], v[72:75], 0
	ds_read_b128 v[172:175], v118 offset:34880
	ds_read_b128 v[176:179], v118 offset:39232
	ds_read_b128 v[180:183], v118 offset:43584
	ds_read_b128 v[184:187], v118 offset:47936
	ds_read_b128 v[188:191], v116 offset:64
	ds_read_b128 v[212:215], v147 offset:64
	ds_read_b128 v[216:219], v147 offset:1152
	s_waitcnt lgkmcnt(8)
	v_mfma_f32_16x16x32_bf16 v[100:103], v[100:103], v[72:75], 0
	s_waitcnt lgkmcnt(7)
	v_mfma_f32_16x16x32_bf16 v[72:75], v[168:171], v[72:75], 0
	ds_read_b128 v[232:235], v147 offset:8768
	ds_read_b128 v[236:239], v147 offset:9856
	s_waitcnt lgkmcnt(4)
	v_mfma_f32_16x16x32_bf16 v[56:59], v[172:175], v[188:191], v[56:59]
	v_mfma_f32_16x16x32_bf16 v[60:63], v[176:179], v[188:191], v[60:63]
	v_mfma_f32_16x16x32_bf16 v[64:67], v[180:183], v[188:191], v[64:67]
	v_mfma_f32_16x16x32_bf16 v[68:71], v[184:187], v[188:191], v[68:71]
	s_waitcnt lgkmcnt(3)
	v_mfma_f32_16x16x32_bf16 v[76:79], v[212:215], v[188:191], v[76:79]
	s_waitcnt lgkmcnt(2)
	v_mfma_f32_16x16x32_bf16 v[96:99], v[216:219], v[188:191], v[96:99]
	ds_read_b128 v[172:175], v118 offset:34944
	ds_read_b128 v[176:179], v118 offset:39296
	ds_read_b128 v[180:183], v118 offset:43648
	ds_read_b128 v[184:187], v118 offset:48000
	ds_read_b128 v[212:215], v116 offset:128
	ds_read_b128 v[216:219], v147 offset:128
	ds_read_b128 v[240:243], v147 offset:1216
	s_waitcnt lgkmcnt(8)
	v_mfma_f32_16x16x32_bf16 v[100:103], v[232:235], v[188:191], v[100:103]
	s_waitcnt lgkmcnt(7)
	v_mfma_f32_16x16x32_bf16 v[72:75], v[236:239], v[188:191], v[72:75]
	ds_read_b128 v[228:231], v147 offset:8832
	ds_read_b128 v[232:235], v147 offset:9920
	s_waitcnt lgkmcnt(4)
	v_mfma_f32_16x16x32_bf16 v[56:59], v[172:175], v[212:215], v[56:59]
	v_mfma_f32_16x16x32_bf16 v[60:63], v[176:179], v[212:215], v[60:63]
	v_mfma_f32_16x16x32_bf16 v[64:67], v[180:183], v[212:215], v[64:67]
	v_mfma_f32_16x16x32_bf16 v[68:71], v[184:187], v[212:215], v[68:71]
	s_waitcnt lgkmcnt(3)
	v_mfma_f32_16x16x32_bf16 v[76:79], v[216:219], v[212:215], v[76:79]
	s_waitcnt lgkmcnt(2)
	v_mfma_f32_16x16x32_bf16 v[172:175], v[240:243], v[212:215], v[96:99]
	s_nop 2
	ds_read_b128 v[96:99], v118 offset:35008
	ds_read_b128 v[176:179], v118 offset:39360
	ds_read_b128 v[180:183], v118 offset:43712
	ds_read_b128 v[184:187], v118 offset:48064
	ds_read_b128 v[216:219], v116 offset:192
	ds_read_b128 v[236:239], v147 offset:192
	ds_read_b128 v[240:243], v147 offset:1280
	s_waitcnt lgkmcnt(8)
	v_mfma_f32_16x16x32_bf16 v[224:227], v[228:231], v[212:215], v[100:103]
	s_waitcnt lgkmcnt(7)
	v_mfma_f32_16x16x32_bf16 v[212:215], v[232:235], v[212:215], v[72:75]
	s_nop 2
	ds_read_b128 v[248:251], v147 offset:8896
	ds_read_b128 v[192:195], v147 offset:9984
	s_waitcnt lgkmcnt(4)
	v_mfma_f32_16x16x32_bf16 v[100:103], v[96:99], v[216:219], v[56:59]
	v_mfma_f32_16x16x32_bf16 v[96:99], v[176:179], v[216:219], v[60:63]
	v_mfma_f32_16x16x32_bf16 v[88:91], v[180:183], v[216:219], v[64:67]
	v_mfma_f32_16x16x32_bf16 v[80:83], v[184:187], v[216:219], v[68:71]
	s_waitcnt lgkmcnt(3)
	v_mfma_f32_16x16x32_bf16 v[68:71], v[236:239], v[216:219], v[76:79]
	s_waitcnt lgkmcnt(2)
	v_mfma_f32_16x16x32_bf16 v[64:67], v[240:243], v[216:219], v[172:175]
	s_waitcnt lgkmcnt(1)
	v_mfma_f32_16x16x32_bf16 v[60:63], v[248:251], v[216:219], v[224:227]
	s_waitcnt lgkmcnt(0)
	v_mfma_f32_16x16x32_bf16 v[56:59], v[192:195], v[216:219], v[212:215]
	s_branch .Lssd_A_join
.Lssd_A_1110:
	v_add_u32_e32 v116, s33, v118
	ds_read_b128 v[56:59], v118 offset:34816
	ds_read_b128 v[60:63], v118 offset:39168
	ds_read_b128 v[64:67], v118 offset:43520
	ds_read_b128 v[68:71], v118 offset:47872
	ds_read_b128 v[72:75], v116
	ds_read_b128 v[76:79], v147
	ds_read_b128 v[80:83], v118 offset:52224
	ds_read_b128 v[84:87], v118 offset:56576
	ds_read_b128 v[96:99], v147 offset:1088
	ds_read_b128 v[100:103], v147 offset:8704
	ds_read_b128 v[168:171], v147 offset:9792
	s_waitcnt lgkmcnt(6)
	v_mfma_f32_16x16x32_bf16 v[56:59], v[56:59], v[72:75], 0
	v_mfma_f32_16x16x32_bf16 v[60:63], v[60:63], v[72:75], 0
	v_mfma_f32_16x16x32_bf16 v[64:67], v[64:67], v[72:75], 0
	v_mfma_f32_16x16x32_bf16 v[68:71], v[68:71], v[72:75], 0
	s_waitcnt lgkmcnt(5)
	v_mfma_f32_16x16x32_bf16 v[76:79], v[76:79], v[72:75], 0
	s_waitcnt lgkmcnt(2)
	v_mfma_f32_16x16x32_bf16 v[96:99], v[96:99], v[72:75], 0
	ds_read_b128 v[172:175], v118 offset:34880
	ds_read_b128 v[176:179], v118 offset:39232
	ds_read_b128 v[180:183], v118 offset:43584
	ds_read_b128 v[184:187], v118 offset:47936
	ds_read_b128 v[188:191], v116 offset:64
	ds_read_b128 v[212:215], v147 offset:64
	ds_read_b128 v[216:219], v147 offset:1152
	v_mfma_f32_16x16x32_bf16 v[80:83], v[80:83], v[72:75], 0
	v_mfma_f32_16x16x32_bf16 v[84:87], v[84:87], v[72:75], 0
	s_waitcnt lgkmcnt(8)
	v_mfma_f32_16x16x32_bf16 v[100:103], v[100:103], v[72:75], 0
	s_waitcnt lgkmcnt(7)
; #define MFMA16(a, b, c) __builtin_amdgcn_mfma_f32_16x16x32_bf16((a), (b), (c), 0, 0, 0)
; __device__ __forceinline__ void phase_C1(const Args& a, unsigned char* ws, const int bid, int l, LAS unsigned char* lds, int tid, int wave, int lane) {
;     ...
;             {
;                 bf16x8 cqv[2], bq[2][4], hq[2][2];
;     ...
;                 SSD_LDH(0, 0);
; #pragma unroll
;                 for (int h2 = 0; h2 < 8; ++h2) { const int cb = h2 & 1, s_ = h2 >> 1, hf_ = h2 & 1;
;                     if (h2 < 7) SSD_LDH(cb ^ 1, h2 + 1);
;                     __builtin_amdgcn_sched_barrier(0);
; #pragma unroll
;                     for (int k = 0; k < 4; ++k) accA[4 * hf_ + k] = MFMA16(bq[cb][k], cqv[s_ & 1], accA[4 * hf_ + k]);
; #pragma unroll
;                     for (int p = 0; p < 2; ++p) accC[2 * hf_ + p] = MFMA16(hq[cb][p], cqv[s_ & 1], accC[2 * hf_ + p]);
;                     __builtin_amdgcn_sched_barrier(0); }
	v_mfma_f32_16x16x32_bf16 v[72:75], v[168:171], v[72:75], 0
	ds_read_b128 v[168:171], v118 offset:52288
	ds_read_b128 v[220:223], v118 offset:56640
	ds_read_b128 v[232:235], v147 offset:8768
	ds_read_b128 v[236:239], v147 offset:9856
	s_waitcnt lgkmcnt(6)
	v_mfma_f32_16x16x32_bf16 v[56:59], v[172:175], v[188:191], v[56:59]
	v_mfma_f32_16x16x32_bf16 v[60:63], v[176:179], v[188:191], v[60:63]
	v_mfma_f32_16x16x32_bf16 v[64:67], v[180:183], v[188:191], v[64:67]
	v_mfma_f32_16x16x32_bf16 v[68:71], v[184:187], v[188:191], v[68:71]
	s_waitcnt lgkmcnt(5)
	v_mfma_f32_16x16x32_bf16 v[76:79], v[212:215], v[188:191], v[76:79]
	s_waitcnt lgkmcnt(4)
	v_mfma_f32_16x16x32_bf16 v[96:99], v[216:219], v[188:191], v[96:99]
	ds_read_b128 v[172:175], v118 offset:34944
	ds_read_b128 v[176:179], v118 offset:39296
	ds_read_b128 v[180:183], v118 offset:43648
	ds_read_b128 v[184:187], v118 offset:48000
	ds_read_b128 v[212:215], v116 offset:128
	ds_read_b128 v[216:219], v147 offset:128
	ds_read_b128 v[240:243], v147 offset:1216
	s_waitcnt lgkmcnt(10)
	v_mfma_f32_16x16x32_bf16 v[80:83], v[168:171], v[188:191], v[80:83]
	s_waitcnt lgkmcnt(9)
	v_mfma_f32_16x16x32_bf16 v[84:87], v[220:223], v[188:191], v[84:87]
	s_waitcnt lgkmcnt(8)
	v_mfma_f32_16x16x32_bf16 v[100:103], v[232:235], v[188:191], v[100:103]
	s_waitcnt lgkmcnt(7)
	v_mfma_f32_16x16x32_bf16 v[72:75], v[236:239], v[188:191], v[72:75]
	ds_read_b128 v[168:171], v118 offset:52352
	ds_read_b128 v[188:191], v118 offset:56704
	ds_read_b128 v[228:231], v147 offset:8832
	ds_read_b128 v[232:235], v147 offset:9920
	s_waitcnt lgkmcnt(6)
	v_mfma_f32_16x16x32_bf16 v[56:59], v[172:175], v[212:215], v[56:59]
	v_mfma_f32_16x16x32_bf16 v[60:63], v[176:179], v[212:215], v[60:63]
	v_mfma_f32_16x16x32_bf16 v[64:67], v[180:183], v[212:215], v[64:67]
	v_mfma_f32_16x16x32_bf16 v[68:71], v[184:187], v[212:215], v[68:71]
	s_waitcnt lgkmcnt(5)
	v_mfma_f32_16x16x32_bf16 v[76:79], v[216:219], v[212:215], v[76:79]
	s_waitcnt lgkmcnt(4)
	v_mfma_f32_16x16x32_bf16 v[172:175], v[240:243], v[212:215], v[96:99]
	s_nop 2
	ds_read_b128 v[96:99], v118 offset:35008
	ds_read_b128 v[176:179], v118 offset:39360
	ds_read_b128 v[180:183], v118 offset:43712
	ds_read_b128 v[184:187], v118 offset:48064
	ds_read_b128 v[216:219], v116 offset:192
	ds_read_b128 v[236:239], v147 offset:192
	ds_read_b128 v[240:243], v147 offset:1280
	s_waitcnt lgkmcnt(10)
	v_mfma_f32_16x16x32_bf16 v[168:171], v[168:171], v[212:215], v[80:83]
	s_waitcnt lgkmcnt(9)
	v_mfma_f32_16x16x32_bf16 v[84:87], v[188:191], v[212:215], v[84:87]
	s_waitcnt lgkmcnt(8)
	v_mfma_f32_16x16x32_bf16 v[224:227], v[228:231], v[212:215], v[100:103]
	s_waitcnt lgkmcnt(7)
	v_mfma_f32_16x16x32_bf16 v[212:215], v[232:235], v[212:215], v[72:75]
	s_nop 2
	ds_read_b128 v[72:75], v118 offset:52416
	ds_read_b128 v[228:231], v118 offset:56768
	ds_read_b128 v[248:251], v147 offset:8896
	ds_read_b128 v[192:195], v147 offset:9984
	s_waitcnt lgkmcnt(6)
	v_mfma_f32_16x16x32_bf16 v[100:103], v[96:99], v[216:219], v[56:59]
	v_mfma_f32_16x16x32_bf16 v[96:99], v[176:179], v[216:219], v[60:63]
	v_mfma_f32_16x16x32_bf16 v[88:91], v[180:183], v[216:219], v[64:67]
	v_mfma_f32_16x16x32_bf16 v[80:83], v[184:187], v[216:219], v[68:71]
	s_waitcnt lgkmcnt(5)
	v_mfma_f32_16x16x32_bf16 v[68:71], v[236:239], v[216:219], v[76:79]
	s_waitcnt lgkmcnt(4)
	v_mfma_f32_16x16x32_bf16 v[64:67], v[240:243], v[216:219], v[172:175]
	s_waitcnt lgkmcnt(3)
	v_mfma_f32_16x16x32_bf16 v[92:95], v[72:75], v[216:219], v[168:171]
	s_waitcnt lgkmcnt(2)
	v_mfma_f32_16x16x32_bf16 v[84:87], v[228:231], v[216:219], v[84:87]
	s_waitcnt lgkmcnt(1)
	v_mfma_f32_16x16x32_bf16 v[60:63], v[248:251], v[216:219], v[224:227]
	s_waitcnt lgkmcnt(0)
	v_mfma_f32_16x16x32_bf16 v[56:59], v[192:195], v[216:219], v[212:215]
	s_branch .Lssd_A_join
.Lssd_A_0111:
	v_add_u32_e32 v116, s33, v118
	ds_read_b128 v[64:67], v118 offset:43520
	ds_read_b128 v[68:71], v118 offset:47872
	ds_read_b128 v[72:75], v116
	ds_read_b128 v[76:79], v147
	ds_read_b128 v[80:83], v118 offset:52224
	ds_read_b128 v[84:87], v118 offset:56576
	ds_read_b128 v[88:91], v118 offset:60928
	ds_read_b128 v[92:95], v118 offset:65280
	ds_read_b128 v[96:99], v147 offset:1088
	ds_read_b128 v[100:103], v147 offset:8704
	ds_read_b128 v[168:171], v147 offset:9792
	s_waitcnt lgkmcnt(8)
	v_mfma_f32_16x16x32_bf16 v[64:67], v[64:67], v[72:75], 0
	v_mfma_f32_16x16x32_bf16 v[68:71], v[68:71], v[72:75], 0
	s_waitcnt lgkmcnt(7)
	v_mfma_f32_16x16x32_bf16 v[76:79], v[76:79], v[72:75], 0
	s_waitcnt lgkmcnt(2)
	v_mfma_f32_16x16x32_bf16 v[96:99], v[96:99], v[72:75], 0
	ds_read_b128 v[180:183], v118 offset:43584
	ds_read_b128 v[184:187], v118 offset:47936
	ds_read_b128 v[188:191], v116 offset:64
	ds_read_b128 v[212:215], v147 offset:64
	ds_read_b128 v[216:219], v147 offset:1152
	v_mfma_f32_16x16x32_bf16 v[80:83], v[80:83], v[72:75], 0
	v_mfma_f32_16x16x32_bf16 v[84:87], v[84:87], v[72:75], 0
	v_mfma_f32_16x16x32_bf16 v[88:91], v[88:91], v[72:75], 0
	v_mfma_f32_16x16x32_bf16 v[92:95], v[92:95], v[72:75], 0
	s_waitcnt lgkmcnt(6)
	v_mfma_f32_16x16x32_bf16 v[100:103], v[100:103], v[72:75], 0
	s_waitcnt lgkmcnt(5)
	v_mfma_f32_16x16x32_bf16 v[72:75], v[168:171], v[72:75], 0
	ds_read_b128 v[168:171], v118 offset:52288
	ds_read_b128 v[220:223], v118 offset:56640
	ds_read_b128 v[224:227], v118 offset:60992
	ds_read_b128 v[228:231], v118 offset:65344
	ds_read_b128 v[232:235], v147 offset:8768
	ds_read_b128 v[236:239], v147 offset:9856
	s_waitcnt lgkmcnt(8)
	v_mfma_f32_16x16x32_bf16 v[64:67], v[180:183], v[188:191], v[64:67]
	v_mfma_f32_16x16x32_bf16 v[68:71], v[184:187], v[188:191], v[68:71]
	s_waitcnt lgkmcnt(7)
; #define MFMA16(a, b, c) __builtin_amdgcn_mfma_f32_16x16x32_bf16((a), (b), (c), 0, 0, 0)
; __device__ __forceinline__ void phase_C1(const Args& a, unsigned char* ws, const int bid, int l, LAS unsigned char* lds, int tid, int wave, int lane) {
;     ...
;             {
;                 bf16x8 cqv[2], bq[2][4], hq[2][2];
;     ...
;                 SSD_LDH(0, 0);
; #pragma unroll
;                 for (int h2 = 0; h2 < 8; ++h2) { const int cb = h2 & 1, s_ = h2 >> 1, hf_ = h2 & 1;
;                     if (h2 < 7) SSD_LDH(cb ^ 1, h2 + 1);
;                     __builtin_amdgcn_sched_barrier(0);
; #pragma unroll
;                     for (int k = 0; k < 4; ++k) accA[4 * hf_ + k] = MFMA16(bq[cb][k], cqv[s_ & 1], accA[4 * hf_ + k]);
; #pragma unroll
;                     for (int p = 0; p < 2; ++p) accC[2 * hf_ + p] = MFMA16(hq[cb][p], cqv[s_ & 1], accC[2 * hf_ + p]);
;                     __builtin_amdgcn_sched_barrier(0); }
	v_mfma_f32_16x16x32_bf16 v[76:79], v[212:215], v[188:191], v[76:79]
	s_waitcnt lgkmcnt(6)
	v_mfma_f32_16x16x32_bf16 v[96:99], v[216:219], v[188:191], v[96:99]
	ds_read_b128 v[180:183], v118 offset:43648
	ds_read_b128 v[184:187], v118 offset:48000
	ds_read_b128 v[212:215], v116 offset:128
	ds_read_b128 v[216:219], v147 offset:128
	ds_read_b128 v[240:243], v147 offset:1216
	s_waitcnt lgkmcnt(10)
	v_mfma_f32_16x16x32_bf16 v[80:83], v[168:171], v[188:191], v[80:83]
	s_waitcnt lgkmcnt(9)
	v_mfma_f32_16x16x32_bf16 v[84:87], v[220:223], v[188:191], v[84:87]
	s_waitcnt lgkmcnt(8)
	v_mfma_f32_16x16x32_bf16 v[88:91], v[224:227], v[188:191], v[88:91]
	s_waitcnt lgkmcnt(7)
	v_mfma_f32_16x16x32_bf16 v[92:95], v[228:231], v[188:191], v[92:95]
	s_waitcnt lgkmcnt(6)
	v_mfma_f32_16x16x32_bf16 v[100:103], v[232:235], v[188:191], v[100:103]
	s_waitcnt lgkmcnt(5)
	v_mfma_f32_16x16x32_bf16 v[72:75], v[236:239], v[188:191], v[72:75]
	ds_read_b128 v[168:171], v118 offset:52352
	ds_read_b128 v[188:191], v118 offset:56704
	ds_read_b128 v[220:223], v118 offset:61056
	ds_read_b128 v[224:227], v118 offset:65408
	ds_read_b128 v[228:231], v147 offset:8832
	ds_read_b128 v[232:235], v147 offset:9920
	s_waitcnt lgkmcnt(8)
	v_mfma_f32_16x16x32_bf16 v[64:67], v[180:183], v[212:215], v[64:67]
	v_mfma_f32_16x16x32_bf16 v[68:71], v[184:187], v[212:215], v[68:71]
	s_waitcnt lgkmcnt(7)
	v_mfma_f32_16x16x32_bf16 v[76:79], v[216:219], v[212:215], v[76:79]
	s_waitcnt lgkmcnt(6)
	v_mfma_f32_16x16x32_bf16 v[172:175], v[240:243], v[212:215], v[96:99]
	s_nop 2
	ds_read_b128 v[180:183], v118 offset:43712
	ds_read_b128 v[184:187], v118 offset:48064
	ds_read_b128 v[216:219], v116 offset:192
	ds_read_b128 v[236:239], v147 offset:192
	ds_read_b128 v[240:243], v147 offset:1280
	s_waitcnt lgkmcnt(10)
	v_mfma_f32_16x16x32_bf16 v[168:171], v[168:171], v[212:215], v[80:83]
	s_waitcnt lgkmcnt(9)
	v_mfma_f32_16x16x32_bf16 v[84:87], v[188:191], v[212:215], v[84:87]
	s_waitcnt lgkmcnt(8)
	v_mfma_f32_16x16x32_bf16 v[188:191], v[220:223], v[212:215], v[88:91]
	s_waitcnt lgkmcnt(7)
	v_mfma_f32_16x16x32_bf16 v[220:223], v[224:227], v[212:215], v[92:95]
	s_waitcnt lgkmcnt(6)
	v_mfma_f32_16x16x32_bf16 v[224:227], v[228:231], v[212:215], v[100:103]
	s_waitcnt lgkmcnt(5)
	v_mfma_f32_16x16x32_bf16 v[212:215], v[232:235], v[212:215], v[72:75]
	s_nop 2
	ds_read_b128 v[72:75], v118 offset:52416
	ds_read_b128 v[228:231], v118 offset:56768
	ds_read_b128 v[232:235], v118 offset:61120
	ds_read_b128 v[244:247], v118 offset:65472
	ds_read_b128 v[248:251], v147 offset:8896
	ds_read_b128 v[192:195], v147 offset:9984
	s_waitcnt lgkmcnt(8)
	v_mfma_f32_16x16x32_bf16 v[88:91], v[180:183], v[216:219], v[64:67]
	v_mfma_f32_16x16x32_bf16 v[80:83], v[184:187], v[216:219], v[68:71]
	s_waitcnt lgkmcnt(7)
	v_mfma_f32_16x16x32_bf16 v[68:71], v[236:239], v[216:219], v[76:79]
	s_waitcnt lgkmcnt(6)
	v_mfma_f32_16x16x32_bf16 v[64:67], v[240:243], v[216:219], v[172:175]
	s_waitcnt lgkmcnt(5)
	v_mfma_f32_16x16x32_bf16 v[92:95], v[72:75], v[216:219], v[168:171]
	s_waitcnt lgkmcnt(4)
	v_mfma_f32_16x16x32_bf16 v[84:87], v[228:231], v[216:219], v[84:87]
	s_waitcnt lgkmcnt(3)
	v_mfma_f32_16x16x32_bf16 v[76:79], v[232:235], v[216:219], v[188:191]
	s_waitcnt lgkmcnt(2)
	v_mfma_f32_16x16x32_bf16 v[72:75], v[244:247], v[216:219], v[220:223]
	s_waitcnt lgkmcnt(1)
	v_mfma_f32_16x16x32_bf16 v[60:63], v[248:251], v[216:219], v[224:227]
	s_waitcnt lgkmcnt(0)
	v_mfma_f32_16x16x32_bf16 v[56:59], v[192:195], v[216:219], v[212:215]
	s_branch .Lssd_A_join
.Lssd_A_0011:
	v_add_u32_e32 v116, s33, v118
	ds_read_b128 v[72:75], v116
	ds_read_b128 v[76:79], v147
	ds_read_b128 v[80:83], v118 offset:52224
	ds_read_b128 v[84:87], v118 offset:56576
	ds_read_b128 v[88:91], v118 offset:60928
	ds_read_b128 v[92:95], v118 offset:65280
	ds_read_b128 v[96:99], v147 offset:1088
	ds_read_b128 v[100:103], v147 offset:8704
	ds_read_b128 v[168:171], v147 offset:9792
	s_waitcnt lgkmcnt(7)
	v_mfma_f32_16x16x32_bf16 v[76:79], v[76:79], v[72:75], 0
	s_waitcnt lgkmcnt(2)
	v_mfma_f32_16x16x32_bf16 v[96:99], v[96:99], v[72:75], 0
	ds_read_b128 v[188:191], v116 offset:64
	ds_read_b128 v[212:215], v147 offset:64
	ds_read_b128 v[216:219], v147 offset:1152
	v_mfma_f32_16x16x32_bf16 v[80:83], v[80:83], v[72:75], 0
	v_mfma_f32_16x16x32_bf16 v[84:87], v[84:87], v[72:75], 0
	v_mfma_f32_16x16x32_bf16 v[88:91], v[88:91], v[72:75], 0
	v_mfma_f32_16x16x32_bf16 v[92:95], v[92:95], v[72:75], 0
	s_waitcnt lgkmcnt(4)
	v_mfma_f32_16x16x32_bf16 v[100:103], v[100:103], v[72:75], 0
	s_waitcnt lgkmcnt(3)
	v_mfma_f32_16x16x32_bf16 v[72:75], v[168:171], v[72:75], 0
	ds_read_b128 v[168:171], v118 offset:52288
	ds_read_b128 v[220:223], v118 offset:56640
	ds_read_b128 v[224:227], v118 offset:60992
	ds_read_b128 v[228:231], v118 offset:65344
	ds_read_b128 v[232:235], v147 offset:8768
	ds_read_b128 v[236:239], v147 offset:9856
	s_waitcnt lgkmcnt(7)
	v_mfma_f32_16x16x32_bf16 v[76:79], v[212:215], v[188:191], v[76:79]
	s_waitcnt lgkmcnt(6)
	v_mfma_f32_16x16x32_bf16 v[96:99], v[216:219], v[188:191], v[96:99]
	ds_read_b128 v[212:215], v116 offset:128
	ds_read_b128 v[216:219], v147 offset:128
	ds_read_b128 v[240:243], v147 offset:1216
	s_waitcnt lgkmcnt(8)
	v_mfma_f32_16x16x32_bf16 v[80:83], v[168:171], v[188:191], v[80:83]
	s_waitcnt lgkmcnt(7)
	v_mfma_f32_16x16x32_bf16 v[84:87], v[220:223], v[188:191], v[84:87]
	s_waitcnt lgkmcnt(6)
	v_mfma_f32_16x16x32_bf16 v[88:91], v[224:227], v[188:191], v[88:91]
	s_waitcnt lgkmcnt(5)
	v_mfma_f32_16x16x32_bf16 v[92:95], v[228:231], v[188:191], v[92:95]
	s_waitcnt lgkmcnt(4)
	v_mfma_f32_16x16x32_bf16 v[100:103], v[232:235], v[188:191], v[100:103]
	s_waitcnt lgkmcnt(3)
; #define MFMA16(a, b, c) __builtin_amdgcn_mfma_f32_16x16x32_bf16((a), (b), (c), 0, 0, 0)
; __device__ __forceinline__ void phase_C1(const Args& a, unsigned char* ws, const int bid, int l, LAS unsigned char* lds, int tid, int wave, int lane) {
;     ...
;             {
;                 bf16x8 cqv[2], bq[2][4], hq[2][2];
;     ...
;                 SSD_LDH(0, 0);
; #pragma unroll
;                 for (int h2 = 0; h2 < 8; ++h2) { const int cb = h2 & 1, s_ = h2 >> 1, hf_ = h2 & 1;
;                     if (h2 < 7) SSD_LDH(cb ^ 1, h2 + 1);
;                     __builtin_amdgcn_sched_barrier(0);
; #pragma unroll
;                     for (int k = 0; k < 4; ++k) accA[4 * hf_ + k] = MFMA16(bq[cb][k], cqv[s_ & 1], accA[4 * hf_ + k]);
; #pragma unroll
;                     for (int p = 0; p < 2; ++p) accC[2 * hf_ + p] = MFMA16(hq[cb][p], cqv[s_ & 1], accC[2 * hf_ + p]);
;                     __builtin_amdgcn_sched_barrier(0); }
	v_mfma_f32_16x16x32_bf16 v[72:75], v[236:239], v[188:191], v[72:75]
	ds_read_b128 v[168:171], v118 offset:52352
	ds_read_b128 v[188:191], v118 offset:56704
	ds_read_b128 v[220:223], v118 offset:61056
	ds_read_b128 v[224:227], v118 offset:65408
	ds_read_b128 v[228:231], v147 offset:8832
	ds_read_b128 v[232:235], v147 offset:9920
	s_waitcnt lgkmcnt(7)
	v_mfma_f32_16x16x32_bf16 v[76:79], v[216:219], v[212:215], v[76:79]
	s_waitcnt lgkmcnt(6)
	v_mfma_f32_16x16x32_bf16 v[172:175], v[240:243], v[212:215], v[96:99]
	s_nop 2
	ds_read_b128 v[216:219], v116 offset:192
	ds_read_b128 v[236:239], v147 offset:192
	ds_read_b128 v[240:243], v147 offset:1280
	s_waitcnt lgkmcnt(8)
	v_mfma_f32_16x16x32_bf16 v[168:171], v[168:171], v[212:215], v[80:83]
	s_waitcnt lgkmcnt(7)
	v_mfma_f32_16x16x32_bf16 v[84:87], v[188:191], v[212:215], v[84:87]
	s_waitcnt lgkmcnt(6)
	v_mfma_f32_16x16x32_bf16 v[188:191], v[220:223], v[212:215], v[88:91]
	s_waitcnt lgkmcnt(5)
	v_mfma_f32_16x16x32_bf16 v[220:223], v[224:227], v[212:215], v[92:95]
	s_waitcnt lgkmcnt(4)
	v_mfma_f32_16x16x32_bf16 v[224:227], v[228:231], v[212:215], v[100:103]
	s_waitcnt lgkmcnt(3)
	v_mfma_f32_16x16x32_bf16 v[212:215], v[232:235], v[212:215], v[72:75]
	s_nop 2
	ds_read_b128 v[72:75], v118 offset:52416
	ds_read_b128 v[228:231], v118 offset:56768
	ds_read_b128 v[232:235], v118 offset:61120
	ds_read_b128 v[244:247], v118 offset:65472
	ds_read_b128 v[248:251], v147 offset:8896
	ds_read_b128 v[192:195], v147 offset:9984
	s_waitcnt lgkmcnt(7)
	v_mfma_f32_16x16x32_bf16 v[68:71], v[236:239], v[216:219], v[76:79]
	s_waitcnt lgkmcnt(6)
	v_mfma_f32_16x16x32_bf16 v[64:67], v[240:243], v[216:219], v[172:175]
	s_waitcnt lgkmcnt(5)
	v_mfma_f32_16x16x32_bf16 v[92:95], v[72:75], v[216:219], v[168:171]
	s_waitcnt lgkmcnt(4)
	v_mfma_f32_16x16x32_bf16 v[84:87], v[228:231], v[216:219], v[84:87]
	s_waitcnt lgkmcnt(3)
	v_mfma_f32_16x16x32_bf16 v[76:79], v[232:235], v[216:219], v[188:191]
	s_waitcnt lgkmcnt(2)
	v_mfma_f32_16x16x32_bf16 v[72:75], v[244:247], v[216:219], v[220:223]
	s_waitcnt lgkmcnt(1)
	v_mfma_f32_16x16x32_bf16 v[60:63], v[248:251], v[216:219], v[224:227]
	s_waitcnt lgkmcnt(0)
	v_mfma_f32_16x16x32_bf16 v[56:59], v[192:195], v[216:219], v[212:215]
	s_branch .Lssd_A_join
.Lssd_A_0001:
	v_add_u32_e32 v116, s33, v118
	ds_read_b128 v[72:75], v116
	ds_read_b128 v[76:79], v147
	ds_read_b128 v[88:91], v118 offset:60928
	ds_read_b128 v[92:95], v118 offset:65280
	ds_read_b128 v[96:99], v147 offset:1088
	ds_read_b128 v[100:103], v147 offset:8704
	ds_read_b128 v[168:171], v147 offset:9792
	s_waitcnt lgkmcnt(5)
	v_mfma_f32_16x16x32_bf16 v[76:79], v[76:79], v[72:75], 0
	s_waitcnt lgkmcnt(2)
	v_mfma_f32_16x16x32_bf16 v[96:99], v[96:99], v[72:75], 0
	ds_read_b128 v[188:191], v116 offset:64
	ds_read_b128 v[212:215], v147 offset:64
	ds_read_b128 v[216:219], v147 offset:1152
	v_mfma_f32_16x16x32_bf16 v[88:91], v[88:91], v[72:75], 0
	v_mfma_f32_16x16x32_bf16 v[92:95], v[92:95], v[72:75], 0
	s_waitcnt lgkmcnt(4)
	v_mfma_f32_16x16x32_bf16 v[100:103], v[100:103], v[72:75], 0
	s_waitcnt lgkmcnt(3)
	v_mfma_f32_16x16x32_bf16 v[72:75], v[168:171], v[72:75], 0
	ds_read_b128 v[224:227], v118 offset:60992
	ds_read_b128 v[228:231], v118 offset:65344
	ds_read_b128 v[232:235], v147 offset:8768
	ds_read_b128 v[236:239], v147 offset:9856
	s_waitcnt lgkmcnt(5)
	v_mfma_f32_16x16x32_bf16 v[76:79], v[212:215], v[188:191], v[76:79]
	s_waitcnt lgkmcnt(4)
	v_mfma_f32_16x16x32_bf16 v[96:99], v[216:219], v[188:191], v[96:99]
	ds_read_b128 v[212:215], v116 offset:128
	ds_read_b128 v[216:219], v147 offset:128
	ds_read_b128 v[240:243], v147 offset:1216
	s_waitcnt lgkmcnt(6)
	v_mfma_f32_16x16x32_bf16 v[88:91], v[224:227], v[188:191], v[88:91]
	s_waitcnt lgkmcnt(5)
	v_mfma_f32_16x16x32_bf16 v[92:95], v[228:231], v[188:191], v[92:95]
	s_waitcnt lgkmcnt(4)
	v_mfma_f32_16x16x32_bf16 v[100:103], v[232:235], v[188:191], v[100:103]
	s_waitcnt lgkmcnt(3)
	v_mfma_f32_16x16x32_bf16 v[72:75], v[236:239], v[188:191], v[72:75]
	ds_read_b128 v[220:223], v118 offset:61056
	ds_read_b128 v[224:227], v118 offset:65408
	ds_read_b128 v[228:231], v147 offset:8832
	ds_read_b128 v[232:235], v147 offset:9920
	s_waitcnt lgkmcnt(5)
	v_mfma_f32_16x16x32_bf16 v[76:79], v[216:219], v[212:215], v[76:79]
	s_waitcnt lgkmcnt(4)
	v_mfma_f32_16x16x32_bf16 v[172:175], v[240:243], v[212:215], v[96:99]
	s_nop 2
	ds_read_b128 v[216:219], v116 offset:192
	ds_read_b128 v[236:239], v147 offset:192
	ds_read_b128 v[240:243], v147 offset:1280
	s_waitcnt lgkmcnt(6)
	v_mfma_f32_16x16x32_bf16 v[188:191], v[220:223], v[212:215], v[88:91]
	s_waitcnt lgkmcnt(5)
	v_mfma_f32_16x16x32_bf16 v[220:223], v[224:227], v[212:215], v[92:95]
	s_waitcnt lgkmcnt(4)
	v_mfma_f32_16x16x32_bf16 v[224:227], v[228:231], v[212:215], v[100:103]
	s_waitcnt lgkmcnt(3)
	v_mfma_f32_16x16x32_bf16 v[212:215], v[232:235], v[212:215], v[72:75]
	s_nop 2
	ds_read_b128 v[232:235], v118 offset:61120
	ds_read_b128 v[244:247], v118 offset:65472
	ds_read_b128 v[248:251], v147 offset:8896
	ds_read_b128 v[192:195], v147 offset:9984
	s_waitcnt lgkmcnt(5)
	v_mfma_f32_16x16x32_bf16 v[68:71], v[236:239], v[216:219], v[76:79]
	s_waitcnt lgkmcnt(4)
	v_mfma_f32_16x16x32_bf16 v[64:67], v[240:243], v[216:219], v[172:175]
	s_waitcnt lgkmcnt(3)
	v_mfma_f32_16x16x32_bf16 v[76:79], v[232:235], v[216:219], v[188:191]
	s_waitcnt lgkmcnt(2)
	v_mfma_f32_16x16x32_bf16 v[72:75], v[244:247], v[216:219], v[220:223]
	s_waitcnt lgkmcnt(1)
	v_mfma_f32_16x16x32_bf16 v[60:63], v[248:251], v[216:219], v[224:227]
	s_waitcnt lgkmcnt(0)
	v_mfma_f32_16x16x32_bf16 v[56:59], v[192:195], v[216:219], v[212:215]
	s_branch .Lssd_A_join
.Lssd_A_join:
	v_readfirstlane_b32 vcc_lo, v164
	s_nop 3
	s_cmp_lt_u32 vcc_lo, 0x100
	s_cbranch_scc1 .Lssd_A_ret_main
	s_branch .Lssd_A_ret_alt
